# X5: X3a (no prio flips, barrier-edge trim in 4 GEMM K-loops) + hand-scheduled SwiGLU epilogue (8 interleaved chains, saddr stores)
# speedup vs baseline: 1.0005x; 1.0005x over previous
; #define PG8_STAGE(bufoff, gbase, voff) do { _Pragma("unroll") for (int _i = 0; _i < 2; ++_i) \
;         __builtin_amdgcn_global_load_lds((const unsigned*)((const char*)(gbase) + (voff)[_i]), (PG8_LAS unsigned*)(lds + (bufoff) + ldsw + _i * 8192), 16, 0, 0); } while (0)
; #define PG8_LDA(dst, b, h) do { _Pragma("unroll") for (int m = 0; m < 4; ++m) _Pragma("unroll") for (int k = 0; k < 2; ++k) dst[m][k] = *(const PG8_LAS bf16x8*)(lds + PG8_SA(b, h) + aoff + m * 2048 + k * 1024); } while (0)
; #define PG8_LDB(dst, b, h) do { _Pragma("unroll") for (int n = 0; n < 2; ++n) _Pragma("unroll") for (int k = 0; k < 2; ++k) dst[n][k] = *(const PG8_LAS bf16x8*)(lds + PG8_SB(b, h) + boff + n * 2048 + k * 1024); } while (0)
; #define PG8_MMA(ai, bj, At, Bt) do { __builtin_amdgcn_s_setprio(1); _Pragma("unroll") for (int m = 0; m < 4; ++m) _Pragma("unroll") for (int n = 0; n < 2; ++n) _Pragma("unroll") for (int k = 0; k < 2; ++k) \
;         acc[ai][bj][m][n] = __builtin_amdgcn_mfma_f32_16x16x32_bf16(Bt[n][k], At[m][k], acc[ai][bj][m][n], 0, 0, 0); __builtin_amdgcn_s_setprio(0); } while (0)
; #define PG8_WAIT_V(n) asm volatile("s_waitcnt vmcnt(" #n ")" ::: "memory")
; #define PG8_WAIT_L(n) asm volatile("s_waitcnt lgkmcnt(" #n ")" ::: "memory")
; template <class Epi, class Sched, bool ALIGN_EPI = false, bool SP2 = false>
; __device__ __forceinline__ void gemm_phase(PG8_LAS unsigned char* lds, const Gemm g, const Sched& S, const Epi& E) {
;     ...
;             const bool last = (t == nt - 2);
;             const char* a1 = cA + (size_t)(t + 1) * kstep;
;             const char* a2 = last ? nA : cA + (size_t)(t + 2) * kstep; const char* b2 = last ? nB : cB + (size_t)(t + 2) * kstep;
;             const char* a3 = a2 + kstep; const char* b3 = b2 + kstep;
;             if (last && has_next) S.a_ready(nxt);
;             if constexpr (SP2) {
;             PG8_LDB(B0, 0, 0); PG8_LDB(B1, 0, 1); PG8_SCHED; PG8_LDA(At, 0, 0); PG8_STAGE(PG8_SA(1, 1), a1 + hstep, voffA);
;             PG8_WAIT_V(8); PG8_WAIT_L(0); PG8_BAR; PG8_MMA(0, 0, At, B0); PG8_MMA(0, 1, At, B1); PG8_BAR; PG8_SCHED;
;             PG8_LDA(At, 0, 1); PG8_STAGE(PG8_SB(0, 0), b2, voffB); PG8_STAGE(PG8_SB(0, 1), b2 + hstep, voffB); PG8_STAGE(PG8_SA(0, 0), a2, voffA);
;             PG8_WAIT_V(8); PG8_WAIT_L(0); PG8_BAR; PG8_MMA(1, 0, At, B0); PG8_MMA(1, 1, At, B1); PG8_BAR; PG8_SCHED;
.LBB0_216:
	s_add_u32 s22, s54, 0xfff80080
	s_addc_u32 s23, s55, -1
	s_add_i32 s34, 0, 0x10000
	s_cmp_eq_u32 s20, 28
	s_cselect_b32 s57, s47, s23
	s_cselect_b32 s56, vcc_lo, s22
	v_add_u32_e32 v152, s34, v155
	s_cselect_b32 s23, s49, s77
	s_cselect_b32 s22, vcc_hi, s71
	s_add_i32 s4, 0, 0x14000
	ds_read_b128 v[144:147], v152
	ds_read_b128 v[148:151], v152 offset:1024
	ds_read_b128 v[168:171], v152 offset:2048
	ds_read_b128 v[172:175], v152 offset:3072
	v_add_u32_e32 v152, s4, v155
	ds_read_b128 v[176:179], v152
	ds_read_b128 v[180:183], v152 offset:1024
	ds_read_b128 v[184:187], v152 offset:2048
	ds_read_b128 v[188:191], v152 offset:3072
	v_lshl_add_u64 v[152:153], s[54:55], 0, v[140:141]
	s_add_i32 m0, s66, 0xc000
	ds_read_b128 v[212:215], v157
	ds_read_b128 v[216:219], v157 offset:1024
	ds_read_b128 v[220:223], v157 offset:2048
	ds_read_b128 v[224:227], v157 offset:3072
	ds_read_b128 v[228:231], v157 offset:4096
	ds_read_b128 v[232:235], v157 offset:5120
	ds_read_b128 v[236:239], v157 offset:6144
	ds_read_b128 v[240:243], v157 offset:7168
	global_load_lds_dwordx4 v[152:153], off
	v_lshl_add_u64 v[152:153], s[54:55], 0, v[142:143]
	s_add_i32 m0, s66, 0xe000
	s_nop 0
	global_load_lds_dwordx4 v[152:153], off
	s_waitcnt vmcnt(8)
	s_waitcnt lgkmcnt(0)
	s_barrier
	v_mfma_f32_16x16x32_bf16 v[126:129], v[144:147], v[212:215], v[126:129]
	v_mfma_f32_16x16x32_bf16 v[118:121], v[168:171], v[212:215], v[118:121]
	v_mfma_f32_16x16x32_bf16 v[110:113], v[144:147], v[220:223], v[110:113]
	v_mfma_f32_16x16x32_bf16 v[102:105], v[168:171], v[220:223], v[102:105]
	v_mfma_f32_16x16x32_bf16 v[94:97], v[144:147], v[228:231], v[94:97]
	v_mfma_f32_16x16x32_bf16 v[86:89], v[168:171], v[228:231], v[86:89]
	v_mfma_f32_16x16x32_bf16 v[78:81], v[144:147], v[236:239], v[78:81]
	v_mfma_f32_16x16x32_bf16 v[70:73], v[168:171], v[236:239], v[70:73]
	v_mfma_f32_16x16x32_bf16 v[126:129], v[148:151], v[216:219], v[126:129]
	v_mfma_f32_16x16x32_bf16 v[118:121], v[172:175], v[216:219], v[118:121]
	v_mfma_f32_16x16x32_bf16 v[110:113], v[148:151], v[224:227], v[110:113]
	v_mfma_f32_16x16x32_bf16 v[102:105], v[172:175], v[224:227], v[102:105]
	v_mfma_f32_16x16x32_bf16 v[94:97], v[148:151], v[232:235], v[94:97]
	v_mfma_f32_16x16x32_bf16 v[86:89], v[172:175], v[232:235], v[86:89]
	v_mfma_f32_16x16x32_bf16 v[78:81], v[148:151], v[240:243], v[78:81]
	v_mfma_f32_16x16x32_bf16 v[70:73], v[172:175], v[240:243], v[70:73]
	v_mfma_f32_16x16x32_bf16 v[130:133], v[176:179], v[212:215], v[130:133]
	v_mfma_f32_16x16x32_bf16 v[122:125], v[184:187], v[212:215], v[122:125]
	v_mfma_f32_16x16x32_bf16 v[114:117], v[176:179], v[220:223], v[114:117]
	v_mfma_f32_16x16x32_bf16 v[106:109], v[184:187], v[220:223], v[106:109]
	v_mfma_f32_16x16x32_bf16 v[98:101], v[176:179], v[228:231], v[98:101]
	v_mfma_f32_16x16x32_bf16 v[90:93], v[184:187], v[228:231], v[90:93]
	v_mfma_f32_16x16x32_bf16 v[82:85], v[176:179], v[236:239], v[82:85]
	v_mfma_f32_16x16x32_bf16 v[74:77], v[184:187], v[236:239], v[74:77]
	v_mfma_f32_16x16x32_bf16 v[130:133], v[180:183], v[216:219], v[130:133]
	v_mfma_f32_16x16x32_bf16 v[122:125], v[188:191], v[216:219], v[122:125]
	v_mfma_f32_16x16x32_bf16 v[114:117], v[180:183], v[224:227], v[114:117]
	v_mfma_f32_16x16x32_bf16 v[106:109], v[188:191], v[224:227], v[106:109]
	v_mfma_f32_16x16x32_bf16 v[98:101], v[180:183], v[232:235], v[98:101]
	v_mfma_f32_16x16x32_bf16 v[90:93], v[188:191], v[232:235], v[90:93]
	v_mfma_f32_16x16x32_bf16 v[82:85], v[180:183], v[240:243], v[82:85]
	v_mfma_f32_16x16x32_bf16 v[74:77], v[188:191], v[240:243], v[74:77]
	s_barrier
	s_add_i32 s5, s34, s65
	v_lshl_add_u64 v[152:153], s[22:23], 0, v[4:5]
	s_mov_b32 m0, s5
	ds_read_b128 v[212:215], v157 offset:16384
	ds_read_b128 v[216:219], v157 offset:17408
	ds_read_b128 v[220:223], v157 offset:18432
	ds_read_b128 v[224:227], v157 offset:19456
	ds_read_b128 v[228:231], v157 offset:20480
	ds_read_b128 v[232:235], v157 offset:21504
	ds_read_b128 v[236:239], v157 offset:22528
	ds_read_b128 v[240:243], v157 offset:23552
	global_load_lds_dwordx4 v[152:153], off
	s_add_i32 m0, s5, 0x2000
	s_add_u32 s34, s22, 0x80000
	v_lshl_add_u64 v[192:193], s[22:23], 0, v[2:3]
	s_addc_u32 s35, s23, 0
	s_add_i32 s4, s4, s65
	global_load_lds_dwordx4 v[192:193], off
	v_lshl_add_u64 v[244:245], s[34:35], 0, v[4:5]
	s_mov_b32 m0, s4
	v_lshl_add_u64 v[246:247], s[56:57], 0, v[134:135]
	global_load_lds_dwordx4 v[244:245], off
	v_lshl_add_u64 v[244:245], s[34:35], 0, v[2:3]
	s_add_i32 m0, s4, 0x2000
	s_nop 0
	global_load_lds_dwordx4 v[244:245], off
	v_lshl_add_u64 v[244:245], s[56:57], 0, v[136:137]
	s_mov_b32 m0, s66
	s_nop 0
	global_load_lds_dwordx4 v[244:245], off
	s_mov_b32 m0, s67
	s_nop 0
	global_load_lds_dwordx4 v[246:247], off
	s_waitcnt vmcnt(8)
	s_waitcnt lgkmcnt(0)
	s_barrier
; #define PG8_STAGE(bufoff, gbase, voff) do { _Pragma("unroll") for (int _i = 0; _i < 2; ++_i) \
;         __builtin_amdgcn_global_load_lds((const unsigned*)((const char*)(gbase) + (voff)[_i]), (PG8_LAS unsigned*)(lds + (bufoff) + ldsw + _i * 8192), 16, 0, 0); } while (0)
; #define PG8_LDA(dst, b, h) do { _Pragma("unroll") for (int m = 0; m < 4; ++m) _Pragma("unroll") for (int k = 0; k < 2; ++k) dst[m][k] = *(const PG8_LAS bf16x8*)(lds + PG8_SA(b, h) + aoff + m * 2048 + k * 1024); } while (0)
; #define PG8_LDB(dst, b, h) do { _Pragma("unroll") for (int n = 0; n < 2; ++n) _Pragma("unroll") for (int k = 0; k < 2; ++k) dst[n][k] = *(const PG8_LAS bf16x8*)(lds + PG8_SB(b, h) + boff + n * 2048 + k * 1024); } while (0)
; #define PG8_MMA(ai, bj, At, Bt) do { __builtin_amdgcn_s_setprio(1); _Pragma("unroll") for (int m = 0; m < 4; ++m) _Pragma("unroll") for (int n = 0; n < 2; ++n) _Pragma("unroll") for (int k = 0; k < 2; ++k) \
;         acc[ai][bj][m][n] = __builtin_amdgcn_mfma_f32_16x16x32_bf16(Bt[n][k], At[m][k], acc[ai][bj][m][n], 0, 0, 0); __builtin_amdgcn_s_setprio(0); } while (0)
; #define PG8_WAIT_V(n) asm volatile("s_waitcnt vmcnt(" #n ")" ::: "memory")
; #define PG8_WAIT_L(n) asm volatile("s_waitcnt lgkmcnt(" #n ")" ::: "memory")
; #define PG8_BAR __builtin_amdgcn_s_barrier()
; #define PG8_SCHED __builtin_amdgcn_sched_barrier(0)
; template <class Epi, class Sched, bool ALIGN_EPI = false, bool SP2 = false>
; __device__ __forceinline__ void gemm_phase(PG8_LAS unsigned char* lds, const Gemm g, const Sched& S, const Epi& E) {
;     ...
;             PG8_WAIT_V(8); PG8_WAIT_L(0); PG8_BAR; PG8_MMA(1, 0, At, B0); PG8_MMA(1, 1, At, B1); PG8_BAR; PG8_SCHED;
;             PG8_LDB(B0, 1, 0); PG8_LDB(B1, 1, 1); PG8_SCHED; PG8_LDA(At, 1, 0); PG8_STAGE(PG8_SA(0, 1), a2 + hstep, voffA);
;             PG8_WAIT_V(8); PG8_WAIT_L(0); PG8_BAR; PG8_MMA(0, 0, At, B0); PG8_MMA(0, 1, At, B1); PG8_BAR; PG8_SCHED;
	v_mfma_f32_16x16x32_bf16 v[62:65], v[144:147], v[212:215], v[62:65]
	v_mfma_f32_16x16x32_bf16 v[54:57], v[168:171], v[212:215], v[54:57]
	v_mfma_f32_16x16x32_bf16 v[46:49], v[144:147], v[220:223], v[46:49]
	v_mfma_f32_16x16x32_bf16 v[38:41], v[168:171], v[220:223], v[38:41]
	v_mfma_f32_16x16x32_bf16 v[30:33], v[144:147], v[228:231], v[30:33]
	v_mfma_f32_16x16x32_bf16 v[22:25], v[168:171], v[228:231], v[22:25]
	v_mfma_f32_16x16x32_bf16 v[14:17], v[144:147], v[236:239], v[14:17]
	v_mfma_f32_16x16x32_bf16 v[6:9], v[168:171], v[236:239], v[6:9]
	v_mfma_f32_16x16x32_bf16 v[62:65], v[148:151], v[216:219], v[62:65]
	v_mfma_f32_16x16x32_bf16 v[54:57], v[172:175], v[216:219], v[54:57]
	v_mfma_f32_16x16x32_bf16 v[46:49], v[148:151], v[224:227], v[46:49]
	v_mfma_f32_16x16x32_bf16 v[38:41], v[172:175], v[224:227], v[38:41]
	v_mfma_f32_16x16x32_bf16 v[30:33], v[148:151], v[232:235], v[30:33]
	v_mfma_f32_16x16x32_bf16 v[22:25], v[172:175], v[232:235], v[22:25]
	v_mfma_f32_16x16x32_bf16 v[14:17], v[148:151], v[240:243], v[14:17]
	v_mfma_f32_16x16x32_bf16 v[6:9], v[172:175], v[240:243], v[6:9]
	v_mfma_f32_16x16x32_bf16 v[66:69], v[176:179], v[212:215], v[66:69]
	v_mfma_f32_16x16x32_bf16 v[58:61], v[184:187], v[212:215], v[58:61]
	v_mfma_f32_16x16x32_bf16 v[50:53], v[176:179], v[220:223], v[50:53]
	v_mfma_f32_16x16x32_bf16 v[42:45], v[184:187], v[220:223], v[42:45]
	v_mfma_f32_16x16x32_bf16 v[34:37], v[176:179], v[228:231], v[34:37]
	v_mfma_f32_16x16x32_bf16 v[26:29], v[184:187], v[228:231], v[26:29]
	v_mfma_f32_16x16x32_bf16 v[18:21], v[176:179], v[236:239], v[18:21]
	v_mfma_f32_16x16x32_bf16 v[10:13], v[184:187], v[236:239], v[10:13]
	v_mfma_f32_16x16x32_bf16 v[66:69], v[180:183], v[216:219], v[66:69]
	v_mfma_f32_16x16x32_bf16 v[58:61], v[188:191], v[216:219], v[58:61]
	v_mfma_f32_16x16x32_bf16 v[50:53], v[180:183], v[224:227], v[50:53]
	v_mfma_f32_16x16x32_bf16 v[42:45], v[188:191], v[224:227], v[42:45]
	v_mfma_f32_16x16x32_bf16 v[34:37], v[180:183], v[232:235], v[34:37]
	v_mfma_f32_16x16x32_bf16 v[26:29], v[188:191], v[232:235], v[26:29]
	v_mfma_f32_16x16x32_bf16 v[18:21], v[180:183], v[240:243], v[18:21]
	v_mfma_f32_16x16x32_bf16 v[10:13], v[188:191], v[240:243], v[10:13]
	s_barrier
	s_add_i32 s4, 0, 0x18000
	v_add_u32_e32 v158, s4, v155
	s_add_i32 s5, 0, 0x1c000
	ds_read_b128 v[144:147], v158
	ds_read_b128 v[148:151], v158 offset:1024
	ds_read_b128 v[168:171], v158 offset:2048
	ds_read_b128 v[172:175], v158 offset:3072
	v_add_u32_e32 v158, s5, v155
	ds_read_b128 v[176:179], v158
	ds_read_b128 v[180:183], v158 offset:1024
	ds_read_b128 v[184:187], v158 offset:2048
	ds_read_b128 v[188:191], v158 offset:3072
	s_add_u32 s34, s56, 0x80000
	s_addc_u32 s35, s57, 0
	s_mov_b32 m0, s60
	v_lshl_add_u64 v[248:249], s[34:35], 0, v[136:137]
	ds_read_b128 v[212:215], v157 offset:32768
	ds_read_b128 v[216:219], v157 offset:33792
	ds_read_b128 v[220:223], v157 offset:34816
	ds_read_b128 v[224:227], v157 offset:35840
	ds_read_b128 v[228:231], v157 offset:36864
	ds_read_b128 v[232:235], v157 offset:37888
	ds_read_b128 v[236:239], v157 offset:38912
	ds_read_b128 v[240:243], v157 offset:39936
	global_load_lds_dwordx4 v[248:249], off
	v_lshl_add_u64 v[248:249], s[34:35], 0, v[134:135]
	s_mov_b32 m0, s2
	s_nop 0
	global_load_lds_dwordx4 v[248:249], off
	s_waitcnt vmcnt(8)
	s_waitcnt lgkmcnt(0)
	s_barrier
	v_mfma_f32_16x16x32_bf16 v[126:129], v[144:147], v[212:215], v[126:129]
	v_mfma_f32_16x16x32_bf16 v[118:121], v[168:171], v[212:215], v[118:121]
	v_mfma_f32_16x16x32_bf16 v[110:113], v[144:147], v[220:223], v[110:113]
	v_mfma_f32_16x16x32_bf16 v[102:105], v[168:171], v[220:223], v[102:105]
	v_mfma_f32_16x16x32_bf16 v[94:97], v[144:147], v[228:231], v[94:97]
	v_mfma_f32_16x16x32_bf16 v[86:89], v[168:171], v[228:231], v[86:89]
	v_mfma_f32_16x16x32_bf16 v[78:81], v[144:147], v[236:239], v[78:81]
	v_mfma_f32_16x16x32_bf16 v[70:73], v[168:171], v[236:239], v[70:73]
	v_mfma_f32_16x16x32_bf16 v[126:129], v[148:151], v[216:219], v[126:129]
	v_mfma_f32_16x16x32_bf16 v[118:121], v[172:175], v[216:219], v[118:121]
	v_mfma_f32_16x16x32_bf16 v[110:113], v[148:151], v[224:227], v[110:113]
	v_mfma_f32_16x16x32_bf16 v[102:105], v[172:175], v[224:227], v[102:105]
	v_mfma_f32_16x16x32_bf16 v[94:97], v[148:151], v[232:235], v[94:97]
	v_mfma_f32_16x16x32_bf16 v[86:89], v[172:175], v[232:235], v[86:89]
	v_mfma_f32_16x16x32_bf16 v[78:81], v[148:151], v[240:243], v[78:81]
	v_mfma_f32_16x16x32_bf16 v[70:73], v[172:175], v[240:243], v[70:73]
	v_mfma_f32_16x16x32_bf16 v[130:133], v[176:179], v[212:215], v[130:133]
	v_mfma_f32_16x16x32_bf16 v[122:125], v[184:187], v[212:215], v[122:125]
	v_mfma_f32_16x16x32_bf16 v[114:117], v[176:179], v[220:223], v[114:117]
	v_mfma_f32_16x16x32_bf16 v[106:109], v[184:187], v[220:223], v[106:109]
	v_mfma_f32_16x16x32_bf16 v[98:101], v[176:179], v[228:231], v[98:101]
	v_mfma_f32_16x16x32_bf16 v[90:93], v[184:187], v[228:231], v[90:93]
	v_mfma_f32_16x16x32_bf16 v[82:85], v[176:179], v[236:239], v[82:85]
	v_mfma_f32_16x16x32_bf16 v[74:77], v[184:187], v[236:239], v[74:77]
	v_mfma_f32_16x16x32_bf16 v[130:133], v[180:183], v[216:219], v[130:133]
	v_mfma_f32_16x16x32_bf16 v[122:125], v[188:191], v[216:219], v[122:125]
	v_mfma_f32_16x16x32_bf16 v[114:117], v[180:183], v[224:227], v[114:117]
	v_mfma_f32_16x16x32_bf16 v[106:109], v[188:191], v[224:227], v[106:109]
	v_mfma_f32_16x16x32_bf16 v[98:101], v[180:183], v[232:235], v[98:101]
	v_mfma_f32_16x16x32_bf16 v[90:93], v[188:191], v[232:235], v[90:93]
	v_mfma_f32_16x16x32_bf16 v[82:85], v[180:183], v[240:243], v[82:85]
	v_mfma_f32_16x16x32_bf16 v[74:77], v[188:191], v[240:243], v[74:77]
	s_barrier
; #define PG8_STAGE(bufoff, gbase, voff) do { _Pragma("unroll") for (int _i = 0; _i < 2; ++_i) \
;         __builtin_amdgcn_global_load_lds((const unsigned*)((const char*)(gbase) + (voff)[_i]), (PG8_LAS unsigned*)(lds + (bufoff) + ldsw + _i * 8192), 16, 0, 0); } while (0)
; #define PG8_LDA(dst, b, h) do { _Pragma("unroll") for (int m = 0; m < 4; ++m) _Pragma("unroll") for (int k = 0; k < 2; ++k) dst[m][k] = *(const PG8_LAS bf16x8*)(lds + PG8_SA(b, h) + aoff + m * 2048 + k * 1024); } while (0)
; #define PG8_MMA(ai, bj, At, Bt) do { __builtin_amdgcn_s_setprio(1); _Pragma("unroll") for (int m = 0; m < 4; ++m) _Pragma("unroll") for (int n = 0; n < 2; ++n) _Pragma("unroll") for (int k = 0; k < 2; ++k) \
;         acc[ai][bj][m][n] = __builtin_amdgcn_mfma_f32_16x16x32_bf16(Bt[n][k], At[m][k], acc[ai][bj][m][n], 0, 0, 0); __builtin_amdgcn_s_setprio(0); } while (0)
; #define PG8_WAIT_V(n) asm volatile("s_waitcnt vmcnt(" #n ")" ::: "memory")
; #define PG8_WAIT_L(n) asm volatile("s_waitcnt lgkmcnt(" #n ")" ::: "memory")
;     __device__ __forceinline__ void operator()(const f32x4 (&acc)[2][2][4][2], const Unit& u, int wr, int wc, int fr, int fq, const Pre& pre) const {
;         const int row0 = u.pm * BM + wr * 64 + fr, col0 = u.pn * HALF + wc * 32 + 8 * fq;
;         unsigned rsv[2][4];
; #pragma unroll
;         for (int ai = 0; ai < 2; ++ai)
; #pragma unroll
;             for (int m = 0; m < 4; ++m) rsv[ai][m] = pre.rs[wr * 64 + fr + ai * HALF + m * 16];
;         __builtin_amdgcn_sched_barrier(0);
; #pragma unroll
;         for (int ai = 0; ai < 2; ++ai)
; #pragma unroll
;             for (int m = 0; m < 4; ++m) { const int row = row0 + ai * HALF + m * 16; const float ms = (float)rsv[ai][m] * inv_d + eps, rl = __builtin_amdgcn_rsqf(ms) * -1.4426950408889634f;
; template <class Epi, class Sched, bool ALIGN_EPI = false, bool SP2 = false>
; __device__ __forceinline__ void gemm_phase(PG8_LAS unsigned char* lds, const Gemm g, const Sched& S, const Epi& E) {
;     ...
;             PG8_WAIT_V(8); PG8_WAIT_L(0); PG8_BAR; PG8_MMA(0, 0, At, B0); PG8_MMA(0, 1, At, B1); PG8_BAR; PG8_SCHED;
;             PG8_LDA(At, 1, 1); PG8_STAGE(PG8_SB(1, 0), b3, voffB); PG8_STAGE(PG8_SB(1, 1), b3 + hstep, voffB); PG8_STAGE(PG8_SA(1, 0), a3, voffA);
;             PG8_WAIT_V(8); PG8_WAIT_L(0); PG8_BAR; PG8_MMA(1, 0, At, B0); PG8_MMA(1, 1, At, B1); PG8_BAR; PG8_SCHED;
	s_add_i32 s4, s4, s65
	v_lshl_add_u64 v[152:153], v[152:153], 0, s[28:29]
	s_mov_b32 m0, s4
	ds_read_b128 v[212:215], v157 offset:49152
	ds_read_b128 v[216:219], v157 offset:50176
	ds_read_b128 v[220:223], v157 offset:51200
	ds_read_b128 v[224:227], v157 offset:52224
	ds_read_b128 v[228:231], v157 offset:53248
	ds_read_b128 v[232:235], v157 offset:54272
	ds_read_b128 v[236:239], v157 offset:55296
	ds_read_b128 v[240:243], v157 offset:56320
	global_load_lds_dwordx4 v[152:153], off
	s_add_i32 m0, s4, 0x2000
	s_add_u32 s22, s22, 0x80080
	v_lshl_add_u64 v[152:153], v[192:193], 0, s[28:29]
	s_addc_u32 s23, s23, 0
	s_add_i32 s4, s5, s65
	global_load_lds_dwordx4 v[152:153], off
	v_lshl_add_u64 v[152:153], s[22:23], 0, v[4:5]
	s_mov_b32 m0, s4
	s_nop 0
	global_load_lds_dwordx4 v[152:153], off
	v_lshl_add_u64 v[152:153], s[22:23], 0, v[2:3]
	s_add_i32 m0, s4, 0x2000
	s_nop 0
	global_load_lds_dwordx4 v[152:153], off
	v_lshl_add_u64 v[152:153], v[244:245], 0, s[28:29]
	s_mov_b32 m0, s3
	s_nop 0
	global_load_lds_dwordx4 v[152:153], off
	v_lshl_add_u64 v[152:153], v[246:247], 0, s[28:29]
	s_mov_b32 m0, s75
	s_nop 0
	global_load_lds_dwordx4 v[152:153], off
	s_waitcnt vmcnt(8)
	s_waitcnt lgkmcnt(0)
	s_barrier
	v_mfma_f32_16x16x32_bf16 v[62:65], v[144:147], v[212:215], v[62:65]
	v_mfma_f32_16x16x32_bf16 v[54:57], v[168:171], v[212:215], v[54:57]
	v_mfma_f32_16x16x32_bf16 v[46:49], v[144:147], v[220:223], v[46:49]
	v_mfma_f32_16x16x32_bf16 v[38:41], v[168:171], v[220:223], v[38:41]
	v_mfma_f32_16x16x32_bf16 v[30:33], v[144:147], v[228:231], v[30:33]
	v_mfma_f32_16x16x32_bf16 v[22:25], v[168:171], v[228:231], v[22:25]
	v_mfma_f32_16x16x32_bf16 v[14:17], v[144:147], v[236:239], v[14:17]
	v_mfma_f32_16x16x32_bf16 v[6:9], v[168:171], v[236:239], v[6:9]
	v_mfma_f32_16x16x32_bf16 v[62:65], v[148:151], v[216:219], v[62:65]
	v_mfma_f32_16x16x32_bf16 v[54:57], v[172:175], v[216:219], v[54:57]
	v_mfma_f32_16x16x32_bf16 v[46:49], v[148:151], v[224:227], v[46:49]
	v_mfma_f32_16x16x32_bf16 v[38:41], v[172:175], v[224:227], v[38:41]
	v_mfma_f32_16x16x32_bf16 v[30:33], v[148:151], v[232:235], v[30:33]
	v_mfma_f32_16x16x32_bf16 v[22:25], v[172:175], v[232:235], v[22:25]
	v_mfma_f32_16x16x32_bf16 v[14:17], v[148:151], v[240:243], v[14:17]
	v_mfma_f32_16x16x32_bf16 v[6:9], v[172:175], v[240:243], v[6:9]
	v_mfma_f32_16x16x32_bf16 v[66:69], v[176:179], v[212:215], v[66:69]
	v_mfma_f32_16x16x32_bf16 v[58:61], v[184:187], v[212:215], v[58:61]
	v_mfma_f32_16x16x32_bf16 v[50:53], v[176:179], v[220:223], v[50:53]
	v_mfma_f32_16x16x32_bf16 v[42:45], v[184:187], v[220:223], v[42:45]
	v_mfma_f32_16x16x32_bf16 v[34:37], v[176:179], v[228:231], v[34:37]
	v_mfma_f32_16x16x32_bf16 v[26:29], v[184:187], v[228:231], v[26:29]
	v_mfma_f32_16x16x32_bf16 v[18:21], v[176:179], v[236:239], v[18:21]
	v_mfma_f32_16x16x32_bf16 v[10:13], v[184:187], v[236:239], v[10:13]
	v_mfma_f32_16x16x32_bf16 v[66:69], v[180:183], v[216:219], v[66:69]
	v_mfma_f32_16x16x32_bf16 v[58:61], v[188:191], v[216:219], v[58:61]
	v_mfma_f32_16x16x32_bf16 v[50:53], v[180:183], v[224:227], v[50:53]
	v_mfma_f32_16x16x32_bf16 v[42:45], v[188:191], v[224:227], v[42:45]
	v_mfma_f32_16x16x32_bf16 v[34:37], v[180:183], v[232:235], v[34:37]
	v_mfma_f32_16x16x32_bf16 v[26:29], v[188:191], v[232:235], v[26:29]
	v_mfma_f32_16x16x32_bf16 v[18:21], v[180:183], v[240:243], v[18:21]
	v_mfma_f32_16x16x32_bf16 v[10:13], v[188:191], v[240:243], v[10:13]
	s_barrier
	s_add_i32 s20, s20, 2
	s_add_u32 s54, s54, 0x100
	s_addc_u32 s55, s55, 0
	s_add_u32 s71, s71, 0x100
	s_addc_u32 s77, s77, 0
	s_cmp_gt_u32 s20, 29
	s_cbranch_scc0 .LBB0_216
	s_and_b64 vcc, exec, s[44:45]
	s_movk_i32 s77, 0x6000
	s_mov_b32 s71, 0x44800000
	s_cbranch_vccz .LBB0_219
	s_barrier
.LBB0_219:
	s_lshl_b32 s4, s72, 2
	s_add_i32 s69, s69, s4
	v_lshl_add_u32 v144, v1, 2, s69
	ds_read2_b32 v[150:151], v144 offset1:16
	ds_read2_b32 v[148:149], v144 offset0:32 offset1:48
	ds_read2_b32 v[146:147], v144 offset0:128 offset1:144
	ds_read2_b32 v[144:145], v144 offset0:160 offset1:176
	v_lshl_add_u32 v158, s74, 8, v154
	v_lshl_or_b32 v152, s33, 7, v156
	s_waitcnt lgkmcnt(0)
	s_movk_i32 s4, 0x2c00
	v_mul_u32_u24_e32 v178, 0x2c00, v158
	v_cvt_f32_u32_e32 v212, v150
	v_cvt_f32_u32_e32 v213, v151
	v_cvt_f32_u32_e32 v214, v148
	v_cvt_f32_u32_e32 v215, v149
	v_cvt_f32_u32_e32 v216, v146
	v_cvt_f32_u32_e32 v217, v147
	v_cvt_f32_u32_e32 v218, v144
	v_cvt_f32_u32_e32 v219, v145
	v_lshl_add_u32 v178, v152, 1, v178
	v_fmamk_f32 v212, v212, 0x35000000, v194
	v_fmamk_f32 v213, v213, 0x35000000, v194
	v_fmamk_f32 v214, v214, 0x35000000, v194
	v_fmamk_f32 v215, v215, 0x35000000, v194
	v_fmamk_f32 v216, v216, 0x35000000, v194
	v_fmamk_f32 v217, v217, 0x35000000, v194
	v_fmamk_f32 v218, v218, 0x35000000, v194
	v_fmamk_f32 v219, v219, 0x35000000, v194
	v_rsq_f32_e32 v220, v212
	v_rsq_f32_e32 v221, v213
	v_rsq_f32_e32 v222, v214
	v_rsq_f32_e32 v223, v215
	v_rsq_f32_e32 v224, v216
	v_rsq_f32_e32 v225, v217
	v_rsq_f32_e32 v226, v218
	v_rsq_f32_e32 v227, v219
	v_mul_f32_e32 v220, 0xbfb8aa3b, v220
	v_mul_f32_e32 v221, 0xbfb8aa3b, v221
	v_mul_f32_e32 v222, 0xbfb8aa3b, v222
	v_mul_f32_e32 v223, 0xbfb8aa3b, v223
	v_mul_f32_e32 v224, 0xbfb8aa3b, v224
	v_mul_f32_e32 v225, 0xbfb8aa3b, v225
	v_mul_f32_e32 v226, 0xbfb8aa3b, v226
	v_mul_f32_e32 v227, 0xbfb8aa3b, v227
	v_mul_f32_e32 v168, v126, v220
	v_mul_f32_e32 v169, v127, v220
	v_mul_f32_e32 v170, v128, v220
	v_mul_f32_e32 v171, v129, v220
	v_mul_f32_e32 v172, v118, v220
	v_mul_f32_e32 v173, v119, v220
	v_mul_f32_e32 v174, v120, v220
	v_mul_f32_e32 v175, v121, v220
	v_exp_f32_e32 v168, v168
	v_exp_f32_e32 v169, v169
	v_exp_f32_e32 v170, v170
	v_exp_f32_e32 v171, v171
; __device__ __forceinline__ unsigned cvt_pk_bf16(float lo, float hi) { unsigned r; asm volatile("v_cvt_pk_bf16_f32 %0, %1, %2" : "=v"(r) : "v"(lo), "v"(hi)); return r; }
;     __device__ __forceinline__ void operator()(const f32x4 (&acc)[2][2][4][2], const Unit& u, int wr, int wc, int fr, int fq, const Pre& pre) const {
;     ...
;             for (int m = 0; m < 4; ++m) { const int row = row0 + ai * HALF + m * 16; const float ms = (float)rsv[ai][m] * inv_d + eps, rl = __builtin_amdgcn_rsqf(ms) * -1.4426950408889634f;
;                 float o[8];
; #pragma unroll
;                 for (int n = 0; n < 2; ++n)
; #pragma unroll
;                     for (int j = 0; j < 4; ++j) { const float g = acc[ai][0][m][n][j], uu = acc[ai][1][m][n][j], t = __builtin_amdgcn_exp2f(g * rl); o[4 * n + j] = (g * uu) * __builtin_amdgcn_rcpf(__builtin_fmaf(t, ms, ms)); }
;                 u32x4 w; w.x = cvt_pk_bf16(o[0], o[1]); w.y = cvt_pk_bf16(o[2], o[3]); w.z = cvt_pk_bf16(o[4], o[5]); w.w = cvt_pk_bf16(o[6], o[7]);
;                 *(u32x4*)(H + (size_t)row * ldh + col0) = w; }
	v_exp_f32_e32 v172, v172
	v_exp_f32_e32 v173, v173
	v_exp_f32_e32 v174, v174
	v_exp_f32_e32 v175, v175
	v_mul_f32_e32 v126, v126, v130
	v_mul_f32_e32 v127, v127, v131
	v_mul_f32_e32 v128, v128, v132
	v_mul_f32_e32 v129, v129, v133
	v_mul_f32_e32 v118, v118, v122
	v_mul_f32_e32 v119, v119, v123
	v_mul_f32_e32 v120, v120, v124
	v_mul_f32_e32 v121, v121, v125
	v_fma_f32 v168, v168, v212, v212
	v_fma_f32 v169, v169, v212, v212
	v_fma_f32 v170, v170, v212, v212
	v_fma_f32 v171, v171, v212, v212
	v_fma_f32 v172, v172, v212, v212
	v_fma_f32 v173, v173, v212, v212
	v_fma_f32 v174, v174, v212, v212
	v_fma_f32 v175, v175, v212, v212
	v_rcp_f32_e32 v168, v168
	v_rcp_f32_e32 v169, v169
	v_rcp_f32_e32 v170, v170
	v_rcp_f32_e32 v171, v171
	v_rcp_f32_e32 v172, v172
	v_rcp_f32_e32 v173, v173
	v_rcp_f32_e32 v174, v174
	v_rcp_f32_e32 v175, v175
	v_mov_b32_e32 v179, v178
	v_mul_f32_e32 v126, v126, v168
	v_mul_f32_e32 v127, v127, v169
	v_mul_f32_e32 v128, v128, v170
	v_mul_f32_e32 v129, v129, v171
	v_mul_f32_e32 v118, v118, v172
	v_mul_f32_e32 v119, v119, v173
	v_mul_f32_e32 v120, v120, v174
	v_mul_f32_e32 v121, v121, v175
	v_cvt_pk_bf16_f32 v180, v126, v127
	v_cvt_pk_bf16_f32 v181, v128, v129
	v_cvt_pk_bf16_f32 v182, v118, v119
	v_cvt_pk_bf16_f32 v183, v120, v121
	global_store_dwordx4 v179, v[180:183], s[26:27]
	v_mul_f32_e32 v168, v110, v221
	v_mul_f32_e32 v169, v111, v221
	v_mul_f32_e32 v170, v112, v221
	v_mul_f32_e32 v171, v113, v221
	v_mul_f32_e32 v172, v102, v221
	v_mul_f32_e32 v173, v103, v221
	v_mul_f32_e32 v174, v104, v221
	v_mul_f32_e32 v175, v105, v221
	v_exp_f32_e32 v168, v168
	v_exp_f32_e32 v169, v169
	v_exp_f32_e32 v170, v170
	v_exp_f32_e32 v171, v171
	v_exp_f32_e32 v172, v172
	v_exp_f32_e32 v173, v173
	v_exp_f32_e32 v174, v174
	v_exp_f32_e32 v175, v175
	v_mul_f32_e32 v110, v110, v114
	v_mul_f32_e32 v111, v111, v115
	v_mul_f32_e32 v112, v112, v116
	v_mul_f32_e32 v113, v113, v117
	v_mul_f32_e32 v102, v102, v106
	v_mul_f32_e32 v103, v103, v107
	v_mul_f32_e32 v104, v104, v108
	v_mul_f32_e32 v105, v105, v109
	v_fma_f32 v168, v168, v213, v213
	v_fma_f32 v169, v169, v213, v213
	v_fma_f32 v170, v170, v213, v213
	v_fma_f32 v171, v171, v213, v213
	v_fma_f32 v172, v172, v213, v213
	v_fma_f32 v173, v173, v213, v213
	v_fma_f32 v174, v174, v213, v213
	v_fma_f32 v175, v175, v213, v213
	v_rcp_f32_e32 v168, v168
	v_rcp_f32_e32 v169, v169
	v_rcp_f32_e32 v170, v170
	v_rcp_f32_e32 v171, v171
	v_rcp_f32_e32 v172, v172
	v_rcp_f32_e32 v173, v173
	v_rcp_f32_e32 v174, v174
	v_rcp_f32_e32 v175, v175
	v_add_u32_e32 v188, 0x2c000, v178
	v_mul_f32_e32 v110, v110, v168
	v_mul_f32_e32 v111, v111, v169
	v_mul_f32_e32 v112, v112, v170
	v_mul_f32_e32 v113, v113, v171
	v_mul_f32_e32 v102, v102, v172
	v_mul_f32_e32 v103, v103, v173
	v_mul_f32_e32 v104, v104, v174
	v_mul_f32_e32 v105, v105, v175
	v_cvt_pk_bf16_f32 v184, v110, v111
	v_cvt_pk_bf16_f32 v185, v112, v113
	v_cvt_pk_bf16_f32 v186, v102, v103
	v_cvt_pk_bf16_f32 v187, v104, v105
	global_store_dwordx4 v188, v[184:187], s[26:27]
	v_mul_f32_e32 v168, v94, v222
	v_mul_f32_e32 v169, v95, v222
	v_mul_f32_e32 v170, v96, v222
	v_mul_f32_e32 v171, v97, v222
	v_mul_f32_e32 v172, v86, v222
	v_mul_f32_e32 v173, v87, v222
	v_mul_f32_e32 v174, v88, v222
	v_mul_f32_e32 v175, v89, v222
	v_exp_f32_e32 v168, v168
	v_exp_f32_e32 v169, v169
	v_exp_f32_e32 v170, v170
	v_exp_f32_e32 v171, v171
	v_exp_f32_e32 v172, v172
	v_exp_f32_e32 v173, v173
	v_exp_f32_e32 v174, v174
	v_exp_f32_e32 v175, v175
	v_mul_f32_e32 v94, v94, v98
	v_mul_f32_e32 v95, v95, v99
	v_mul_f32_e32 v96, v96, v100
	v_mul_f32_e32 v97, v97, v101
	v_mul_f32_e32 v86, v86, v90
	v_mul_f32_e32 v87, v87, v91
	v_mul_f32_e32 v88, v88, v92
	v_mul_f32_e32 v89, v89, v93
	v_fma_f32 v168, v168, v214, v214
	v_fma_f32 v169, v169, v214, v214
	v_fma_f32 v170, v170, v214, v214
	v_fma_f32 v171, v171, v214, v214
	v_fma_f32 v172, v172, v214, v214
	v_fma_f32 v173, v173, v214, v214
	v_fma_f32 v174, v174, v214, v214
	v_fma_f32 v175, v175, v214, v214
	v_rcp_f32_e32 v168, v168
	v_rcp_f32_e32 v169, v169
	v_rcp_f32_e32 v170, v170
	v_rcp_f32_e32 v171, v171
	v_rcp_f32_e32 v172, v172
	v_rcp_f32_e32 v173, v173
	v_rcp_f32_e32 v174, v174
	v_rcp_f32_e32 v175, v175
	v_add_u32_e32 v179, 0x58000, v178
	v_mul_f32_e32 v94, v94, v168
	v_mul_f32_e32 v95, v95, v169
	v_mul_f32_e32 v96, v96, v170
	v_mul_f32_e32 v97, v97, v171
	v_mul_f32_e32 v86, v86, v172
	v_mul_f32_e32 v87, v87, v173
	v_mul_f32_e32 v88, v88, v174
	v_mul_f32_e32 v89, v89, v175
	v_cvt_pk_bf16_f32 v180, v94, v95
	v_cvt_pk_bf16_f32 v181, v96, v97
	v_cvt_pk_bf16_f32 v182, v86, v87
	v_cvt_pk_bf16_f32 v183, v88, v89
	global_store_dwordx4 v179, v[180:183], s[26:27]
	v_mul_f32_e32 v168, v78, v223
	v_mul_f32_e32 v169, v79, v223
	v_mul_f32_e32 v170, v80, v223
	v_mul_f32_e32 v171, v81, v223
	v_mul_f32_e32 v172, v70, v223
	v_mul_f32_e32 v173, v71, v223
	v_mul_f32_e32 v174, v72, v223
	v_mul_f32_e32 v175, v73, v223
	v_exp_f32_e32 v168, v168
	v_exp_f32_e32 v169, v169
	v_exp_f32_e32 v170, v170
	v_exp_f32_e32 v171, v171
	v_exp_f32_e32 v172, v172
	v_exp_f32_e32 v173, v173
	v_exp_f32_e32 v174, v174
	v_exp_f32_e32 v175, v175
	v_mul_f32_e32 v78, v78, v82
	v_mul_f32_e32 v79, v79, v83
	v_mul_f32_e32 v80, v80, v84
	v_mul_f32_e32 v81, v81, v85
	v_mul_f32_e32 v70, v70, v74
	v_mul_f32_e32 v71, v71, v75
	v_mul_f32_e32 v72, v72, v76
	v_mul_f32_e32 v73, v73, v77
	v_fma_f32 v168, v168, v215, v215
	v_fma_f32 v169, v169, v215, v215
	v_fma_f32 v170, v170, v215, v215
	v_fma_f32 v171, v171, v215, v215
	v_fma_f32 v172, v172, v215, v215
	v_fma_f32 v173, v173, v215, v215
	v_fma_f32 v174, v174, v215, v215
	v_fma_f32 v175, v175, v215, v215
	v_rcp_f32_e32 v168, v168
	v_rcp_f32_e32 v169, v169
; __device__ __forceinline__ unsigned cvt_pk_bf16(float lo, float hi) { unsigned r; asm volatile("v_cvt_pk_bf16_f32 %0, %1, %2" : "=v"(r) : "v"(lo), "v"(hi)); return r; }
;     __device__ __forceinline__ void operator()(const f32x4 (&acc)[2][2][4][2], const Unit& u, int wr, int wc, int fr, int fq, const Pre& pre) const {
;     ...
;             for (int m = 0; m < 4; ++m) { const int row = row0 + ai * HALF + m * 16; const float ms = (float)rsv[ai][m] * inv_d + eps, rl = __builtin_amdgcn_rsqf(ms) * -1.4426950408889634f;
;                 float o[8];
; #pragma unroll
;                 for (int n = 0; n < 2; ++n)
; #pragma unroll
;                     for (int j = 0; j < 4; ++j) { const float g = acc[ai][0][m][n][j], uu = acc[ai][1][m][n][j], t = __builtin_amdgcn_exp2f(g * rl); o[4 * n + j] = (g * uu) * __builtin_amdgcn_rcpf(__builtin_fmaf(t, ms, ms)); }
;                 u32x4 w; w.x = cvt_pk_bf16(o[0], o[1]); w.y = cvt_pk_bf16(o[2], o[3]); w.z = cvt_pk_bf16(o[4], o[5]); w.w = cvt_pk_bf16(o[6], o[7]);
;                 *(u32x4*)(H + (size_t)row * ldh + col0) = w; }
	v_rcp_f32_e32 v170, v170
	v_rcp_f32_e32 v171, v171
	v_rcp_f32_e32 v172, v172
	v_rcp_f32_e32 v173, v173
	v_rcp_f32_e32 v174, v174
	v_rcp_f32_e32 v175, v175
	v_add_u32_e32 v188, 0x84000, v178
	v_mul_f32_e32 v78, v78, v168
	v_mul_f32_e32 v79, v79, v169
	v_mul_f32_e32 v80, v80, v170
	v_mul_f32_e32 v81, v81, v171
	v_mul_f32_e32 v70, v70, v172
	v_mul_f32_e32 v71, v71, v173
	v_mul_f32_e32 v72, v72, v174
	v_mul_f32_e32 v73, v73, v175
	v_cvt_pk_bf16_f32 v184, v78, v79
	v_cvt_pk_bf16_f32 v185, v80, v81
	v_cvt_pk_bf16_f32 v186, v70, v71
	v_cvt_pk_bf16_f32 v187, v72, v73
	global_store_dwordx4 v188, v[184:187], s[26:27]
	v_mul_f32_e32 v168, v62, v224
	v_mul_f32_e32 v169, v63, v224
	v_mul_f32_e32 v170, v64, v224
	v_mul_f32_e32 v171, v65, v224
	v_mul_f32_e32 v172, v54, v224
	v_mul_f32_e32 v173, v55, v224
	v_mul_f32_e32 v174, v56, v224
	v_mul_f32_e32 v175, v57, v224
	v_exp_f32_e32 v168, v168
	v_exp_f32_e32 v169, v169
	v_exp_f32_e32 v170, v170
	v_exp_f32_e32 v171, v171
	v_exp_f32_e32 v172, v172
	v_exp_f32_e32 v173, v173
	v_exp_f32_e32 v174, v174
	v_exp_f32_e32 v175, v175
	v_mul_f32_e32 v62, v62, v66
	v_mul_f32_e32 v63, v63, v67
	v_mul_f32_e32 v64, v64, v68
	v_mul_f32_e32 v65, v65, v69
	v_mul_f32_e32 v54, v54, v58
	v_mul_f32_e32 v55, v55, v59
	v_mul_f32_e32 v56, v56, v60
	v_mul_f32_e32 v57, v57, v61
	v_fma_f32 v168, v168, v216, v216
	v_fma_f32 v169, v169, v216, v216
	v_fma_f32 v170, v170, v216, v216
	v_fma_f32 v171, v171, v216, v216
	v_fma_f32 v172, v172, v216, v216
	v_fma_f32 v173, v173, v216, v216
	v_fma_f32 v174, v174, v216, v216
	v_fma_f32 v175, v175, v216, v216
	v_rcp_f32_e32 v168, v168
	v_rcp_f32_e32 v169, v169
	v_rcp_f32_e32 v170, v170
	v_rcp_f32_e32 v171, v171
	v_rcp_f32_e32 v172, v172
	v_rcp_f32_e32 v173, v173
	v_rcp_f32_e32 v174, v174
	v_rcp_f32_e32 v175, v175
	v_add_u32_e32 v179, 0x160000, v178
	v_mul_f32_e32 v62, v62, v168
	v_mul_f32_e32 v63, v63, v169
	v_mul_f32_e32 v64, v64, v170
	v_mul_f32_e32 v65, v65, v171
	v_mul_f32_e32 v54, v54, v172
	v_mul_f32_e32 v55, v55, v173
	v_mul_f32_e32 v56, v56, v174
	v_mul_f32_e32 v57, v57, v175
	v_cvt_pk_bf16_f32 v180, v62, v63
	v_cvt_pk_bf16_f32 v181, v64, v65
	v_cvt_pk_bf16_f32 v182, v54, v55
	v_cvt_pk_bf16_f32 v183, v56, v57
	global_store_dwordx4 v179, v[180:183], s[26:27]
	v_mul_f32_e32 v168, v46, v225
	v_mul_f32_e32 v169, v47, v225
	v_mul_f32_e32 v170, v48, v225
	v_mul_f32_e32 v171, v49, v225
	v_mul_f32_e32 v172, v38, v225
	v_mul_f32_e32 v173, v39, v225
	v_mul_f32_e32 v174, v40, v225
	v_mul_f32_e32 v175, v41, v225
	v_exp_f32_e32 v168, v168
	v_exp_f32_e32 v169, v169
	v_exp_f32_e32 v170, v170
	v_exp_f32_e32 v171, v171
	v_exp_f32_e32 v172, v172
	v_exp_f32_e32 v173, v173
	v_exp_f32_e32 v174, v174
	v_exp_f32_e32 v175, v175
	v_mul_f32_e32 v46, v46, v50
	v_mul_f32_e32 v47, v47, v51
	v_mul_f32_e32 v48, v48, v52
	v_mul_f32_e32 v49, v49, v53
	v_mul_f32_e32 v38, v38, v42
	v_mul_f32_e32 v39, v39, v43
	v_mul_f32_e32 v40, v40, v44
	v_mul_f32_e32 v41, v41, v45
	v_fma_f32 v168, v168, v217, v217
	v_fma_f32 v169, v169, v217, v217
	v_fma_f32 v170, v170, v217, v217
	v_fma_f32 v171, v171, v217, v217
	v_fma_f32 v172, v172, v217, v217
	v_fma_f32 v173, v173, v217, v217
	v_fma_f32 v174, v174, v217, v217
	v_fma_f32 v175, v175, v217, v217
	v_rcp_f32_e32 v168, v168
	v_rcp_f32_e32 v169, v169
	v_rcp_f32_e32 v170, v170
	v_rcp_f32_e32 v171, v171
	v_rcp_f32_e32 v172, v172
	v_rcp_f32_e32 v173, v173
	v_rcp_f32_e32 v174, v174
	v_rcp_f32_e32 v175, v175
	v_add_u32_e32 v188, 0x18c000, v178
	v_mul_f32_e32 v46, v46, v168
	v_mul_f32_e32 v47, v47, v169
	v_mul_f32_e32 v48, v48, v170
	v_mul_f32_e32 v49, v49, v171
	v_mul_f32_e32 v38, v38, v172
	v_mul_f32_e32 v39, v39, v173
	v_mul_f32_e32 v40, v40, v174
	v_mul_f32_e32 v41, v41, v175
	v_cvt_pk_bf16_f32 v184, v46, v47
	v_cvt_pk_bf16_f32 v185, v48, v49
	v_cvt_pk_bf16_f32 v186, v38, v39
	v_cvt_pk_bf16_f32 v187, v40, v41
	global_store_dwordx4 v188, v[184:187], s[26:27]
	v_mul_f32_e32 v168, v30, v226
	v_mul_f32_e32 v169, v31, v226
	v_mul_f32_e32 v170, v32, v226
	v_mul_f32_e32 v171, v33, v226
	v_mul_f32_e32 v172, v22, v226
	v_mul_f32_e32 v173, v23, v226
	v_mul_f32_e32 v174, v24, v226
	v_mul_f32_e32 v175, v25, v226
	v_exp_f32_e32 v168, v168
	v_exp_f32_e32 v169, v169
	v_exp_f32_e32 v170, v170
	v_exp_f32_e32 v171, v171
	v_exp_f32_e32 v172, v172
	v_exp_f32_e32 v173, v173
	v_exp_f32_e32 v174, v174
	v_exp_f32_e32 v175, v175
	v_mul_f32_e32 v30, v30, v34
	v_mul_f32_e32 v31, v31, v35
; __device__ __forceinline__ unsigned cvt_pk_bf16(float lo, float hi) { unsigned r; asm volatile("v_cvt_pk_bf16_f32 %0, %1, %2" : "=v"(r) : "v"(lo), "v"(hi)); return r; }
; #define PG8_BAR __builtin_amdgcn_s_barrier()
;     __device__ __forceinline__ void operator()(const f32x4 (&acc)[2][2][4][2], const Unit& u, int wr, int wc, int fr, int fq, const Pre& pre) const {
;     ...
;             for (int m = 0; m < 4; ++m) { const int row = row0 + ai * HALF + m * 16; const float ms = (float)rsv[ai][m] * inv_d + eps, rl = __builtin_amdgcn_rsqf(ms) * -1.4426950408889634f;
;                 float o[8];
; #pragma unroll
;                 for (int n = 0; n < 2; ++n)
; #pragma unroll
;                     for (int j = 0; j < 4; ++j) { const float g = acc[ai][0][m][n][j], uu = acc[ai][1][m][n][j], t = __builtin_amdgcn_exp2f(g * rl); o[4 * n + j] = (g * uu) * __builtin_amdgcn_rcpf(__builtin_fmaf(t, ms, ms)); }
;                 u32x4 w; w.x = cvt_pk_bf16(o[0], o[1]); w.y = cvt_pk_bf16(o[2], o[3]); w.z = cvt_pk_bf16(o[4], o[5]); w.w = cvt_pk_bf16(o[6], o[7]);
;                 *(u32x4*)(H + (size_t)row * ldh + col0) = w; }
; template <class Epi, class Sched, bool ALIGN_EPI = false, bool SP2 = false>
; __device__ __forceinline__ void gemm_phase(PG8_LAS unsigned char* lds, const Gemm g, const Sched& S, const Epi& E) {
;     ...
;         if (!has_next) break;
;         PG8_ZERO_ACC();
;         cur = nxt; cA = nA; cB = nB; ++ui;
;         if constexpr (ALIGN_EPI) { if (wr == 1) PG8_BAR; }
	v_mul_f32_e32 v32, v32, v36
	v_mul_f32_e32 v33, v33, v37
	v_mul_f32_e32 v22, v22, v26
	v_mul_f32_e32 v23, v23, v27
	v_mul_f32_e32 v24, v24, v28
	v_mul_f32_e32 v25, v25, v29
	v_fma_f32 v168, v168, v218, v218
	v_fma_f32 v169, v169, v218, v218
	v_fma_f32 v170, v170, v218, v218
	v_fma_f32 v171, v171, v218, v218
	v_fma_f32 v172, v172, v218, v218
	v_fma_f32 v173, v173, v218, v218
	v_fma_f32 v174, v174, v218, v218
	v_fma_f32 v175, v175, v218, v218
	v_rcp_f32_e32 v168, v168
	v_rcp_f32_e32 v169, v169
	v_rcp_f32_e32 v170, v170
	v_rcp_f32_e32 v171, v171
	v_rcp_f32_e32 v172, v172
	v_rcp_f32_e32 v173, v173
	v_rcp_f32_e32 v174, v174
	v_rcp_f32_e32 v175, v175
	v_add_u32_e32 v179, 0x1b8000, v178
	v_mul_f32_e32 v30, v30, v168
	v_mul_f32_e32 v31, v31, v169
	v_mul_f32_e32 v32, v32, v170
	v_mul_f32_e32 v33, v33, v171
	v_mul_f32_e32 v22, v22, v172
	v_mul_f32_e32 v23, v23, v173
	v_mul_f32_e32 v24, v24, v174
	v_mul_f32_e32 v25, v25, v175
	v_cvt_pk_bf16_f32 v180, v30, v31
	v_cvt_pk_bf16_f32 v181, v32, v33
	v_cvt_pk_bf16_f32 v182, v22, v23
	v_cvt_pk_bf16_f32 v183, v24, v25
	global_store_dwordx4 v179, v[180:183], s[26:27]
	v_mul_f32_e32 v168, v14, v227
	v_mul_f32_e32 v169, v15, v227
	v_mul_f32_e32 v170, v16, v227
	v_mul_f32_e32 v171, v17, v227
	v_mul_f32_e32 v172, v6, v227
	v_mul_f32_e32 v173, v7, v227
	v_mul_f32_e32 v174, v8, v227
	v_mul_f32_e32 v175, v9, v227
	v_exp_f32_e32 v168, v168
	v_exp_f32_e32 v169, v169
	v_exp_f32_e32 v170, v170
	v_exp_f32_e32 v171, v171
	v_exp_f32_e32 v172, v172
	v_exp_f32_e32 v173, v173
	v_exp_f32_e32 v174, v174
	v_exp_f32_e32 v175, v175
	v_mul_f32_e32 v14, v14, v18
	v_mul_f32_e32 v15, v15, v19
	v_mul_f32_e32 v16, v16, v20
	v_mul_f32_e32 v17, v17, v21
	v_mul_f32_e32 v6, v6, v10
	v_mul_f32_e32 v7, v7, v11
	v_mul_f32_e32 v8, v8, v12
	v_mul_f32_e32 v9, v9, v13
	v_fma_f32 v168, v168, v219, v219
	v_fma_f32 v169, v169, v219, v219
	v_fma_f32 v170, v170, v219, v219
	v_fma_f32 v171, v171, v219, v219
	v_fma_f32 v172, v172, v219, v219
	v_fma_f32 v173, v173, v219, v219
	v_fma_f32 v174, v174, v219, v219
	v_fma_f32 v175, v175, v219, v219
	v_rcp_f32_e32 v168, v168
	v_rcp_f32_e32 v169, v169
	v_rcp_f32_e32 v170, v170
	v_rcp_f32_e32 v171, v171
	v_rcp_f32_e32 v172, v172
	v_rcp_f32_e32 v173, v173
	v_rcp_f32_e32 v174, v174
	v_rcp_f32_e32 v175, v175
	v_add_u32_e32 v188, 0x1e4000, v178
	v_mul_f32_e32 v14, v14, v168
	v_mul_f32_e32 v15, v15, v169
	v_mul_f32_e32 v16, v16, v170
	v_mul_f32_e32 v17, v17, v171
	v_mul_f32_e32 v6, v6, v172
	v_mul_f32_e32 v7, v7, v173
	v_mul_f32_e32 v8, v8, v174
	v_mul_f32_e32 v9, v9, v175
	v_cvt_pk_bf16_f32 v184, v14, v15
	v_cvt_pk_bf16_f32 v185, v16, v17
	v_cvt_pk_bf16_f32 v186, v6, v7
	v_cvt_pk_bf16_f32 v187, v8, v9
	global_store_dwordx4 v188, v[184:187], s[26:27]
	s_mov_b64 s[22:23], -1
	s_andn2_b64 vcc, exec, s[36:37]
	s_cbranch_vccnz .LBB0_210
	s_andn2_b64 vcc, exec, s[38:39]
	v_mov_b64 v[126:127], 0
	v_mov_b64 v[128:129], 0
	v_mov_b64 v[118:119], 0
	v_mov_b64 v[120:121], 0
	v_mov_b64 v[110:111], 0
	v_mov_b64 v[112:113], 0
	v_mov_b64 v[102:103], 0
	v_mov_b64 v[104:105], 0
	v_mov_b64 v[94:95], 0
	v_mov_b64 v[96:97], 0
	v_mov_b64 v[86:87], 0
	v_mov_b64 v[88:89], 0
	v_mov_b64 v[78:79], 0
	v_mov_b64 v[80:81], 0
	v_mov_b64 v[70:71], 0
	v_mov_b64 v[72:73], 0
	v_mov_b64 v[130:131], 0
	v_mov_b64 v[132:133], 0
	v_mov_b64 v[122:123], 0
	v_mov_b64 v[124:125], 0
	v_mov_b64 v[114:115], 0
	v_mov_b64 v[116:117], 0
	v_mov_b64 v[106:107], 0
	v_mov_b64 v[108:109], 0
	v_mov_b64 v[98:99], 0
	v_mov_b64 v[100:101], 0
	v_mov_b64 v[90:91], 0
	v_mov_b64 v[92:93], 0
	v_mov_b64 v[82:83], 0
	v_mov_b64 v[84:85], 0
	v_mov_b64 v[74:75], 0
	v_mov_b64 v[76:77], 0
	v_mov_b64 v[62:63], 0
	v_mov_b64 v[64:65], 0
	v_mov_b64 v[54:55], 0
	v_mov_b64 v[56:57], 0
	v_mov_b64 v[46:47], 0
	v_mov_b64 v[48:49], 0
	v_mov_b64 v[38:39], 0
	v_mov_b64 v[40:41], 0
	v_mov_b64 v[30:31], 0
	v_mov_b64 v[32:33], 0
	v_mov_b64 v[22:23], 0
	v_mov_b64 v[24:25], 0
	v_mov_b64 v[14:15], 0
	v_mov_b64 v[16:17], 0
	v_mov_b64 v[6:7], 0
	v_mov_b64 v[8:9], 0
	v_mov_b64 v[66:67], 0
	v_mov_b64 v[68:69], 0
	v_mov_b64 v[58:59], 0
	v_mov_b64 v[60:61], 0
	v_mov_b64 v[50:51], 0
	v_mov_b64 v[52:53], 0
	v_mov_b64 v[42:43], 0
	v_mov_b64 v[44:45], 0
	v_mov_b64 v[34:35], 0
	v_mov_b64 v[36:37], 0
	v_mov_b64 v[26:27], 0
	v_mov_b64 v[28:29], 0
	v_mov_b64 v[18:19], 0
	v_mov_b64 v[20:21], 0
	v_mov_b64 v[10:11], 0
	v_mov_b64 v[12:13], 0
	s_cbranch_vccnz .LBB0_209
	s_barrier
	s_branch .LBB0_209

; #define PG8_STAGE(bufoff, gbase, voff) do { _Pragma("unroll") for (int _i = 0; _i < 2; ++_i) \
;         __builtin_amdgcn_global_load_lds((const unsigned*)((const char*)(gbase) + (voff)[_i]), (PG8_LAS unsigned*)(lds + (bufoff) + ldsw + _i * 8192), 16, 0, 0); } while (0)
; #define PG8_LDA(dst, b, h) do { _Pragma("unroll") for (int m = 0; m < 4; ++m) _Pragma("unroll") for (int k = 0; k < 2; ++k) dst[m][k] = *(const PG8_LAS bf16x8*)(lds + PG8_SA(b, h) + aoff + m * 2048 + k * 1024); } while (0)
; #define PG8_LDB(dst, b, h) do { _Pragma("unroll") for (int n = 0; n < 2; ++n) _Pragma("unroll") for (int k = 0; k < 2; ++k) dst[n][k] = *(const PG8_LAS bf16x8*)(lds + PG8_SB(b, h) + boff + n * 2048 + k * 1024); } while (0)
; #define PG8_MMA(ai, bj, At, Bt) do { __builtin_amdgcn_s_setprio(1); _Pragma("unroll") for (int m = 0; m < 4; ++m) _Pragma("unroll") for (int n = 0; n < 2; ++n) _Pragma("unroll") for (int k = 0; k < 2; ++k) \
;         acc[ai][bj][m][n] = __builtin_amdgcn_mfma_f32_16x16x32_bf16(Bt[n][k], At[m][k], acc[ai][bj][m][n], 0, 0, 0); __builtin_amdgcn_s_setprio(0); } while (0)
; #define PG8_WAIT_V(n) asm volatile("s_waitcnt vmcnt(" #n ")" ::: "memory")
; #define PG8_WAIT_L(n) asm volatile("s_waitcnt lgkmcnt(" #n ")" ::: "memory")
; template <class Epi, class Sched, bool ALIGN_EPI = false, bool SP2 = false>
; __device__ __forceinline__ void gemm_phase(PG8_LAS unsigned char* lds, const Gemm g, const Sched& S, const Epi& E) {
;     ...
;             const bool last = (t == nt - 2);
;             const char* a1 = cA + (size_t)(t + 1) * kstep;
;             const char* a2 = last ? nA : cA + (size_t)(t + 2) * kstep; const char* b2 = last ? nB : cB + (size_t)(t + 2) * kstep;
;             const char* a3 = a2 + kstep; const char* b3 = b2 + kstep;
;             if (last && has_next) S.a_ready(nxt);
;             if constexpr (SP2) {
;             PG8_LDB(B0, 0, 0); PG8_LDB(B1, 0, 1); PG8_SCHED; PG8_LDA(At, 0, 0); PG8_STAGE(PG8_SA(1, 1), a1 + hstep, voffA);
;             PG8_WAIT_V(8); PG8_WAIT_L(0); PG8_BAR; PG8_MMA(0, 0, At, B0); PG8_MMA(0, 1, At, B1); PG8_BAR; PG8_SCHED;
;             PG8_LDA(At, 0, 1); PG8_STAGE(PG8_SB(0, 0), b2, voffB); PG8_STAGE(PG8_SB(0, 1), b2 + hstep, voffB); PG8_STAGE(PG8_SA(0, 0), a2, voffA);
;             PG8_WAIT_V(8); PG8_WAIT_L(0); PG8_BAR; PG8_MMA(1, 0, At, B0); PG8_MMA(1, 1, At, B1); PG8_BAR; PG8_SCHED;
.LBB0_299:
	s_add_u32 s50, s22, 0x100
	s_addc_u32 s51, s23, 0
	s_add_i32 s4, 0, 0x10000
	s_cmpk_eq_i32 s20, 0x54
	s_cselect_b32 s55, s41, s51
	s_cselect_b32 s54, s40, s50
	s_cselect_b32 s53, s49, s69
	s_cselect_b32 s52, s48, s33
	s_add_i32 s5, 0, 0x14000
	v_add_u32_e32 v146, s4, v158
	v_add_u32_e32 v180, s5, v158
	ds_read_b128 v[134:137], v146
	ds_read_b128 v[138:141], v146 offset:1024
	ds_read_b128 v[142:145], v146 offset:2048
	ds_read_b128 v[146:149], v146 offset:3072
	ds_read_b128 v[150:153], v180
	ds_read_b128 v[154:157], v180 offset:1024
	ds_read_b128 v[176:179], v180 offset:2048
	ds_read_b128 v[180:183], v180 offset:3072
	v_lshl_add_u64 v[236:237], s[22:23], 0, v[172:173]
	s_add_i32 m0, s56, 0xc000
	ds_read_b128 v[184:187], v188
	ds_read_b128 v[190:193], v188 offset:1024
	ds_read_b128 v[212:215], v188 offset:2048
	ds_read_b128 v[216:219], v188 offset:3072
	ds_read_b128 v[220:223], v188 offset:4096
	ds_read_b128 v[224:227], v188 offset:5120
	ds_read_b128 v[228:231], v188 offset:6144
	ds_read_b128 v[232:235], v188 offset:7168
	global_load_lds_dwordx4 v[236:237], off
	v_lshl_add_u64 v[236:237], s[22:23], 0, v[174:175]
	s_add_i32 m0, s56, 0xe000
	s_nop 0
	global_load_lds_dwordx4 v[236:237], off
	s_waitcnt vmcnt(8)
	s_waitcnt lgkmcnt(0)
	s_barrier
	v_mfma_f32_16x16x32_bf16 v[122:125], v[134:137], v[184:187], v[122:125]
	v_mfma_f32_16x16x32_bf16 v[118:121], v[142:145], v[184:187], v[118:121]
	v_mfma_f32_16x16x32_bf16 v[114:117], v[134:137], v[212:215], v[114:117]
	v_mfma_f32_16x16x32_bf16 v[110:113], v[142:145], v[212:215], v[110:113]
	v_mfma_f32_16x16x32_bf16 v[98:101], v[134:137], v[220:223], v[98:101]
	v_mfma_f32_16x16x32_bf16 v[94:97], v[142:145], v[220:223], v[94:97]
	v_mfma_f32_16x16x32_bf16 v[82:85], v[134:137], v[228:231], v[82:85]
	v_mfma_f32_16x16x32_bf16 v[78:81], v[142:145], v[228:231], v[78:81]
	v_mfma_f32_16x16x32_bf16 v[122:125], v[138:141], v[190:193], v[122:125]
	v_mfma_f32_16x16x32_bf16 v[118:121], v[146:149], v[190:193], v[118:121]
	v_mfma_f32_16x16x32_bf16 v[114:117], v[138:141], v[216:219], v[114:117]
	v_mfma_f32_16x16x32_bf16 v[110:113], v[146:149], v[216:219], v[110:113]
	v_mfma_f32_16x16x32_bf16 v[98:101], v[138:141], v[224:227], v[98:101]
	v_mfma_f32_16x16x32_bf16 v[94:97], v[146:149], v[224:227], v[94:97]
	v_mfma_f32_16x16x32_bf16 v[82:85], v[138:141], v[232:235], v[82:85]
	v_mfma_f32_16x16x32_bf16 v[78:81], v[146:149], v[232:235], v[78:81]
	v_mfma_f32_16x16x32_bf16 v[130:133], v[150:153], v[184:187], v[130:133]
	v_mfma_f32_16x16x32_bf16 v[126:129], v[176:179], v[184:187], v[126:129]
	v_mfma_f32_16x16x32_bf16 v[106:109], v[150:153], v[212:215], v[106:109]
	v_mfma_f32_16x16x32_bf16 v[102:105], v[176:179], v[212:215], v[102:105]
	v_mfma_f32_16x16x32_bf16 v[90:93], v[150:153], v[220:223], v[90:93]
	v_mfma_f32_16x16x32_bf16 v[86:89], v[176:179], v[220:223], v[86:89]
	v_mfma_f32_16x16x32_bf16 v[74:77], v[150:153], v[228:231], v[74:77]
	v_mfma_f32_16x16x32_bf16 v[70:73], v[176:179], v[228:231], v[70:73]
	v_mfma_f32_16x16x32_bf16 v[130:133], v[154:157], v[190:193], v[130:133]
	v_mfma_f32_16x16x32_bf16 v[126:129], v[180:183], v[190:193], v[126:129]
	v_mfma_f32_16x16x32_bf16 v[106:109], v[154:157], v[216:219], v[106:109]
	v_mfma_f32_16x16x32_bf16 v[102:105], v[180:183], v[216:219], v[102:105]
	v_mfma_f32_16x16x32_bf16 v[90:93], v[154:157], v[224:227], v[90:93]
	v_mfma_f32_16x16x32_bf16 v[86:89], v[180:183], v[224:227], v[86:89]
	v_mfma_f32_16x16x32_bf16 v[74:77], v[154:157], v[232:235], v[74:77]
	v_mfma_f32_16x16x32_bf16 v[70:73], v[180:183], v[232:235], v[70:73]
	s_barrier
	s_add_i32 s4, s4, s24
	v_lshl_add_u64 v[236:237], s[52:53], 0, v[4:5]
	s_mov_b32 m0, s4
	ds_read_b128 v[184:187], v188 offset:16384
	ds_read_b128 v[190:193], v188 offset:17408
	ds_read_b128 v[212:215], v188 offset:18432
	ds_read_b128 v[216:219], v188 offset:19456
	ds_read_b128 v[220:223], v188 offset:20480
	ds_read_b128 v[224:227], v188 offset:21504
	ds_read_b128 v[228:231], v188 offset:22528
	ds_read_b128 v[232:235], v188 offset:23552
	global_load_lds_dwordx4 v[236:237], off
	s_add_i32 m0, s4, 0x2000
	s_add_u32 s22, s52, 0x160000
	v_lshl_add_u64 v[238:239], s[52:53], 0, v[170:171]
	s_addc_u32 s23, s53, 0
	s_add_i32 s4, s5, s24
	global_load_lds_dwordx4 v[238:239], off
	v_lshl_add_u64 v[240:241], s[22:23], 0, v[4:5]
	s_mov_b32 m0, s4
	v_lshl_add_u64 v[242:243], s[54:55], 0, v[168:169]
	global_load_lds_dwordx4 v[240:241], off
	v_lshl_add_u64 v[240:241], s[22:23], 0, v[170:171]
	s_add_i32 m0, s4, 0x2000
	s_nop 0
	global_load_lds_dwordx4 v[240:241], off
	v_lshl_add_u64 v[240:241], s[54:55], 0, v[2:3]
	s_mov_b32 m0, s56
	s_nop 0
	global_load_lds_dwordx4 v[240:241], off
	s_mov_b32 m0, s57
	s_nop 0
	global_load_lds_dwordx4 v[242:243], off
	s_waitcnt vmcnt(8)
	s_waitcnt lgkmcnt(0)
	s_barrier
; #define PG8_STAGE(bufoff, gbase, voff) do { _Pragma("unroll") for (int _i = 0; _i < 2; ++_i) \
;         __builtin_amdgcn_global_load_lds((const unsigned*)((const char*)(gbase) + (voff)[_i]), (PG8_LAS unsigned*)(lds + (bufoff) + ldsw + _i * 8192), 16, 0, 0); } while (0)
; #define PG8_LDA(dst, b, h) do { _Pragma("unroll") for (int m = 0; m < 4; ++m) _Pragma("unroll") for (int k = 0; k < 2; ++k) dst[m][k] = *(const PG8_LAS bf16x8*)(lds + PG8_SA(b, h) + aoff + m * 2048 + k * 1024); } while (0)
; #define PG8_LDB(dst, b, h) do { _Pragma("unroll") for (int n = 0; n < 2; ++n) _Pragma("unroll") for (int k = 0; k < 2; ++k) dst[n][k] = *(const PG8_LAS bf16x8*)(lds + PG8_SB(b, h) + boff + n * 2048 + k * 1024); } while (0)
; #define PG8_MMA(ai, bj, At, Bt) do { __builtin_amdgcn_s_setprio(1); _Pragma("unroll") for (int m = 0; m < 4; ++m) _Pragma("unroll") for (int n = 0; n < 2; ++n) _Pragma("unroll") for (int k = 0; k < 2; ++k) \
;         acc[ai][bj][m][n] = __builtin_amdgcn_mfma_f32_16x16x32_bf16(Bt[n][k], At[m][k], acc[ai][bj][m][n], 0, 0, 0); __builtin_amdgcn_s_setprio(0); } while (0)
; #define PG8_WAIT_V(n) asm volatile("s_waitcnt vmcnt(" #n ")" ::: "memory")
; #define PG8_WAIT_L(n) asm volatile("s_waitcnt lgkmcnt(" #n ")" ::: "memory")
; #define PG8_BAR __builtin_amdgcn_s_barrier()
; #define PG8_SCHED __builtin_amdgcn_sched_barrier(0)
; template <class Epi, class Sched, bool ALIGN_EPI = false, bool SP2 = false>
; __device__ __forceinline__ void gemm_phase(PG8_LAS unsigned char* lds, const Gemm g, const Sched& S, const Epi& E) {
;     ...
;             PG8_WAIT_V(8); PG8_WAIT_L(0); PG8_BAR; PG8_MMA(1, 0, At, B0); PG8_MMA(1, 1, At, B1); PG8_BAR; PG8_SCHED;
;             PG8_LDB(B0, 1, 0); PG8_LDB(B1, 1, 1); PG8_SCHED; PG8_LDA(At, 1, 0); PG8_STAGE(PG8_SA(0, 1), a2 + hstep, voffA);
;             PG8_WAIT_V(8); PG8_WAIT_L(0); PG8_BAR; PG8_MMA(0, 0, At, B0); PG8_MMA(0, 1, At, B1); PG8_BAR; PG8_SCHED;
	v_mfma_f32_16x16x32_bf16 v[58:61], v[134:137], v[184:187], v[58:61]
	v_mfma_f32_16x16x32_bf16 v[54:57], v[142:145], v[184:187], v[54:57]
	v_mfma_f32_16x16x32_bf16 v[50:53], v[134:137], v[212:215], v[50:53]
	v_mfma_f32_16x16x32_bf16 v[46:49], v[142:145], v[212:215], v[46:49]
	v_mfma_f32_16x16x32_bf16 v[34:37], v[134:137], v[220:223], v[34:37]
	v_mfma_f32_16x16x32_bf16 v[30:33], v[142:145], v[220:223], v[30:33]
	v_mfma_f32_16x16x32_bf16 v[18:21], v[134:137], v[228:231], v[18:21]
	v_mfma_f32_16x16x32_bf16 v[14:17], v[142:145], v[228:231], v[14:17]
	v_mfma_f32_16x16x32_bf16 v[58:61], v[138:141], v[190:193], v[58:61]
	v_mfma_f32_16x16x32_bf16 v[54:57], v[146:149], v[190:193], v[54:57]
	v_mfma_f32_16x16x32_bf16 v[50:53], v[138:141], v[216:219], v[50:53]
	v_mfma_f32_16x16x32_bf16 v[46:49], v[146:149], v[216:219], v[46:49]
	v_mfma_f32_16x16x32_bf16 v[34:37], v[138:141], v[224:227], v[34:37]
	v_mfma_f32_16x16x32_bf16 v[30:33], v[146:149], v[224:227], v[30:33]
	v_mfma_f32_16x16x32_bf16 v[18:21], v[138:141], v[232:235], v[18:21]
	v_mfma_f32_16x16x32_bf16 v[14:17], v[146:149], v[232:235], v[14:17]
	v_mfma_f32_16x16x32_bf16 v[66:69], v[150:153], v[184:187], v[66:69]
	v_mfma_f32_16x16x32_bf16 v[62:65], v[176:179], v[184:187], v[62:65]
	v_mfma_f32_16x16x32_bf16 v[42:45], v[150:153], v[212:215], v[42:45]
	v_mfma_f32_16x16x32_bf16 v[38:41], v[176:179], v[212:215], v[38:41]
	v_mfma_f32_16x16x32_bf16 v[26:29], v[150:153], v[220:223], v[26:29]
	v_mfma_f32_16x16x32_bf16 v[22:25], v[176:179], v[220:223], v[22:25]
	v_mfma_f32_16x16x32_bf16 v[10:13], v[150:153], v[228:231], v[10:13]
	v_mfma_f32_16x16x32_bf16 v[6:9], v[176:179], v[228:231], v[6:9]
	v_mfma_f32_16x16x32_bf16 v[66:69], v[154:157], v[190:193], v[66:69]
	v_mfma_f32_16x16x32_bf16 v[62:65], v[180:183], v[190:193], v[62:65]
	v_mfma_f32_16x16x32_bf16 v[42:45], v[154:157], v[216:219], v[42:45]
	v_mfma_f32_16x16x32_bf16 v[38:41], v[180:183], v[216:219], v[38:41]
	v_mfma_f32_16x16x32_bf16 v[26:29], v[154:157], v[224:227], v[26:29]
	v_mfma_f32_16x16x32_bf16 v[22:25], v[180:183], v[224:227], v[22:25]
	v_mfma_f32_16x16x32_bf16 v[10:13], v[154:157], v[232:235], v[10:13]
	v_mfma_f32_16x16x32_bf16 v[6:9], v[180:183], v[232:235], v[6:9]
	s_barrier
	s_add_i32 s4, 0, 0x18000
	s_add_i32 s5, 0, 0x1c000
	v_add_u32_e32 v146, s4, v158
	v_add_u32_e32 v180, s5, v158
	ds_read_b128 v[134:137], v146
	ds_read_b128 v[138:141], v146 offset:1024
	ds_read_b128 v[142:145], v146 offset:2048
	ds_read_b128 v[146:149], v146 offset:3072
	ds_read_b128 v[150:153], v180
	ds_read_b128 v[154:157], v180 offset:1024
	ds_read_b128 v[176:179], v180 offset:2048
	ds_read_b128 v[180:183], v180 offset:3072
	s_add_u32 s22, s54, 0x160000
	s_addc_u32 s23, s55, 0
	s_mov_b32 m0, s59
	v_lshl_add_u64 v[244:245], s[22:23], 0, v[2:3]
	ds_read_b128 v[184:187], v188 offset:32768
	ds_read_b128 v[190:193], v188 offset:33792
	ds_read_b128 v[212:215], v188 offset:34816
	ds_read_b128 v[216:219], v188 offset:35840
	ds_read_b128 v[220:223], v188 offset:36864
	ds_read_b128 v[224:227], v188 offset:37888
	ds_read_b128 v[228:231], v188 offset:38912
	ds_read_b128 v[232:235], v188 offset:39936
	global_load_lds_dwordx4 v[244:245], off
	v_lshl_add_u64 v[244:245], s[22:23], 0, v[168:169]
	s_mov_b32 m0, s60
	s_nop 0
	global_load_lds_dwordx4 v[244:245], off
	s_waitcnt vmcnt(8)
	s_waitcnt lgkmcnt(0)
	s_barrier
	v_mfma_f32_16x16x32_bf16 v[122:125], v[134:137], v[184:187], v[122:125]
	v_mfma_f32_16x16x32_bf16 v[118:121], v[142:145], v[184:187], v[118:121]
	v_mfma_f32_16x16x32_bf16 v[114:117], v[134:137], v[212:215], v[114:117]
	v_mfma_f32_16x16x32_bf16 v[110:113], v[142:145], v[212:215], v[110:113]
	v_mfma_f32_16x16x32_bf16 v[98:101], v[134:137], v[220:223], v[98:101]
	v_mfma_f32_16x16x32_bf16 v[94:97], v[142:145], v[220:223], v[94:97]
	v_mfma_f32_16x16x32_bf16 v[82:85], v[134:137], v[228:231], v[82:85]
	v_mfma_f32_16x16x32_bf16 v[78:81], v[142:145], v[228:231], v[78:81]
	v_mfma_f32_16x16x32_bf16 v[122:125], v[138:141], v[190:193], v[122:125]
	v_mfma_f32_16x16x32_bf16 v[118:121], v[146:149], v[190:193], v[118:121]
	v_mfma_f32_16x16x32_bf16 v[114:117], v[138:141], v[216:219], v[114:117]
	v_mfma_f32_16x16x32_bf16 v[110:113], v[146:149], v[216:219], v[110:113]
	v_mfma_f32_16x16x32_bf16 v[98:101], v[138:141], v[224:227], v[98:101]
	v_mfma_f32_16x16x32_bf16 v[94:97], v[146:149], v[224:227], v[94:97]
	v_mfma_f32_16x16x32_bf16 v[82:85], v[138:141], v[232:235], v[82:85]
	v_mfma_f32_16x16x32_bf16 v[78:81], v[146:149], v[232:235], v[78:81]
	v_mfma_f32_16x16x32_bf16 v[130:133], v[150:153], v[184:187], v[130:133]
	v_mfma_f32_16x16x32_bf16 v[126:129], v[176:179], v[184:187], v[126:129]
	v_mfma_f32_16x16x32_bf16 v[106:109], v[150:153], v[212:215], v[106:109]
	v_mfma_f32_16x16x32_bf16 v[102:105], v[176:179], v[212:215], v[102:105]
	v_mfma_f32_16x16x32_bf16 v[90:93], v[150:153], v[220:223], v[90:93]
	v_mfma_f32_16x16x32_bf16 v[86:89], v[176:179], v[220:223], v[86:89]
	v_mfma_f32_16x16x32_bf16 v[74:77], v[150:153], v[228:231], v[74:77]
	v_mfma_f32_16x16x32_bf16 v[70:73], v[176:179], v[228:231], v[70:73]
	v_mfma_f32_16x16x32_bf16 v[130:133], v[154:157], v[190:193], v[130:133]
	v_mfma_f32_16x16x32_bf16 v[126:129], v[180:183], v[190:193], v[126:129]
	v_mfma_f32_16x16x32_bf16 v[106:109], v[154:157], v[216:219], v[106:109]
	v_mfma_f32_16x16x32_bf16 v[102:105], v[180:183], v[216:219], v[102:105]
	v_mfma_f32_16x16x32_bf16 v[90:93], v[154:157], v[224:227], v[90:93]
	v_mfma_f32_16x16x32_bf16 v[86:89], v[180:183], v[224:227], v[86:89]
	v_mfma_f32_16x16x32_bf16 v[74:77], v[154:157], v[232:235], v[74:77]
	v_mfma_f32_16x16x32_bf16 v[70:73], v[180:183], v[232:235], v[70:73]
	s_barrier
; #define PG8_STAGE(bufoff, gbase, voff) do { _Pragma("unroll") for (int _i = 0; _i < 2; ++_i) \
;         __builtin_amdgcn_global_load_lds((const unsigned*)((const char*)(gbase) + (voff)[_i]), (PG8_LAS unsigned*)(lds + (bufoff) + ldsw + _i * 8192), 16, 0, 0); } while (0)
; #define PG8_LDA(dst, b, h) do { _Pragma("unroll") for (int m = 0; m < 4; ++m) _Pragma("unroll") for (int k = 0; k < 2; ++k) dst[m][k] = *(const PG8_LAS bf16x8*)(lds + PG8_SA(b, h) + aoff + m * 2048 + k * 1024); } while (0)
; #define PG8_MMA(ai, bj, At, Bt) do { __builtin_amdgcn_s_setprio(1); _Pragma("unroll") for (int m = 0; m < 4; ++m) _Pragma("unroll") for (int n = 0; n < 2; ++n) _Pragma("unroll") for (int k = 0; k < 2; ++k) \
;         acc[ai][bj][m][n] = __builtin_amdgcn_mfma_f32_16x16x32_bf16(Bt[n][k], At[m][k], acc[ai][bj][m][n], 0, 0, 0); __builtin_amdgcn_s_setprio(0); } while (0)
; #define PG8_WAIT_V(n) asm volatile("s_waitcnt vmcnt(" #n ")" ::: "memory")
; #define PG8_WAIT_L(n) asm volatile("s_waitcnt lgkmcnt(" #n ")" ::: "memory")
; #define PG8_BAR __builtin_amdgcn_s_barrier()
; #define PG8_SCHED __builtin_amdgcn_sched_barrier(0)
; template <class Epi, class Sched, bool ALIGN_EPI = false, bool SP2 = false>
; __device__ __forceinline__ void gemm_phase(PG8_LAS unsigned char* lds, const Gemm g, const Sched& S, const Epi& E) {
;     ...
;             PG8_WAIT_V(8); PG8_WAIT_L(0); PG8_BAR; PG8_MMA(0, 0, At, B0); PG8_MMA(0, 1, At, B1); PG8_BAR; PG8_SCHED;
;             PG8_LDA(At, 1, 1); PG8_STAGE(PG8_SB(1, 0), b3, voffB); PG8_STAGE(PG8_SB(1, 1), b3 + hstep, voffB); PG8_STAGE(PG8_SA(1, 0), a3, voffA);
;             PG8_WAIT_V(8); PG8_WAIT_L(0); PG8_BAR; PG8_MMA(1, 0, At, B0); PG8_MMA(1, 1, At, B1); PG8_BAR; PG8_SCHED;
	s_add_i32 s4, s4, s24
	v_lshl_add_u64 v[236:237], v[236:237], 0, s[28:29]
	s_mov_b32 m0, s4
	ds_read_b128 v[184:187], v188 offset:49152
	ds_read_b128 v[190:193], v188 offset:50176
	ds_read_b128 v[212:215], v188 offset:51200
	ds_read_b128 v[216:219], v188 offset:52224
	ds_read_b128 v[220:223], v188 offset:53248
	ds_read_b128 v[224:227], v188 offset:54272
	ds_read_b128 v[228:231], v188 offset:55296
	ds_read_b128 v[232:235], v188 offset:56320
	global_load_lds_dwordx4 v[236:237], off
	s_add_i32 m0, s4, 0x2000
	s_add_u32 s22, s52, 0x160080
	v_lshl_add_u64 v[236:237], v[238:239], 0, s[28:29]
	s_addc_u32 s23, s53, 0
	s_add_i32 s4, s5, s24
	global_load_lds_dwordx4 v[236:237], off
	v_lshl_add_u64 v[236:237], s[22:23], 0, v[4:5]
	s_mov_b32 m0, s4
	s_nop 0
	global_load_lds_dwordx4 v[236:237], off
	v_lshl_add_u64 v[236:237], s[22:23], 0, v[170:171]
	s_add_i32 m0, s4, 0x2000
	s_nop 0
	global_load_lds_dwordx4 v[236:237], off
	v_lshl_add_u64 v[236:237], v[240:241], 0, s[28:29]
	s_mov_b32 m0, s61
	s_nop 0
	global_load_lds_dwordx4 v[236:237], off
	v_lshl_add_u64 v[236:237], v[242:243], 0, s[28:29]
	s_mov_b32 m0, s64
	s_nop 0
	global_load_lds_dwordx4 v[236:237], off
	s_waitcnt vmcnt(8)
	s_waitcnt lgkmcnt(0)
	s_barrier
	v_mfma_f32_16x16x32_bf16 v[58:61], v[134:137], v[184:187], v[58:61]
	v_mfma_f32_16x16x32_bf16 v[54:57], v[142:145], v[184:187], v[54:57]
	v_mfma_f32_16x16x32_bf16 v[50:53], v[134:137], v[212:215], v[50:53]
	v_mfma_f32_16x16x32_bf16 v[46:49], v[142:145], v[212:215], v[46:49]
	v_mfma_f32_16x16x32_bf16 v[34:37], v[134:137], v[220:223], v[34:37]
	v_mfma_f32_16x16x32_bf16 v[30:33], v[142:145], v[220:223], v[30:33]
	v_mfma_f32_16x16x32_bf16 v[18:21], v[134:137], v[228:231], v[18:21]
	v_mfma_f32_16x16x32_bf16 v[14:17], v[142:145], v[228:231], v[14:17]
	v_mfma_f32_16x16x32_bf16 v[58:61], v[138:141], v[190:193], v[58:61]
	v_mfma_f32_16x16x32_bf16 v[54:57], v[146:149], v[190:193], v[54:57]
	v_mfma_f32_16x16x32_bf16 v[50:53], v[138:141], v[216:219], v[50:53]
	v_mfma_f32_16x16x32_bf16 v[46:49], v[146:149], v[216:219], v[46:49]
	v_mfma_f32_16x16x32_bf16 v[34:37], v[138:141], v[224:227], v[34:37]
	v_mfma_f32_16x16x32_bf16 v[30:33], v[146:149], v[224:227], v[30:33]
	v_mfma_f32_16x16x32_bf16 v[18:21], v[138:141], v[232:235], v[18:21]
	v_mfma_f32_16x16x32_bf16 v[14:17], v[146:149], v[232:235], v[14:17]
	v_mfma_f32_16x16x32_bf16 v[66:69], v[150:153], v[184:187], v[66:69]
	v_mfma_f32_16x16x32_bf16 v[62:65], v[176:179], v[184:187], v[62:65]
	v_mfma_f32_16x16x32_bf16 v[42:45], v[150:153], v[212:215], v[42:45]
	v_mfma_f32_16x16x32_bf16 v[38:41], v[176:179], v[212:215], v[38:41]
	v_mfma_f32_16x16x32_bf16 v[26:29], v[150:153], v[220:223], v[26:29]
	v_mfma_f32_16x16x32_bf16 v[22:25], v[176:179], v[220:223], v[22:25]
	v_mfma_f32_16x16x32_bf16 v[10:13], v[150:153], v[228:231], v[10:13]
	v_mfma_f32_16x16x32_bf16 v[6:9], v[176:179], v[228:231], v[6:9]
	v_mfma_f32_16x16x32_bf16 v[66:69], v[154:157], v[190:193], v[66:69]
	v_mfma_f32_16x16x32_bf16 v[62:65], v[180:183], v[190:193], v[62:65]
	v_mfma_f32_16x16x32_bf16 v[42:45], v[154:157], v[216:219], v[42:45]
	v_mfma_f32_16x16x32_bf16 v[38:41], v[180:183], v[216:219], v[38:41]
	v_mfma_f32_16x16x32_bf16 v[26:29], v[154:157], v[224:227], v[26:29]
	v_mfma_f32_16x16x32_bf16 v[22:25], v[180:183], v[224:227], v[22:25]
	v_mfma_f32_16x16x32_bf16 v[10:13], v[154:157], v[232:235], v[10:13]
	v_mfma_f32_16x16x32_bf16 v[6:9], v[180:183], v[232:235], v[6:9]
	s_barrier
	s_add_i32 s20, s20, 2
	s_add_u32 s33, s33, 0x100
	s_addc_u32 s69, s69, 0
	s_cmpk_gt_u32 s20, 0x55
	s_mov_b64 s[22:23], s[50:51]
	s_cbranch_scc0 .LBB0_299
	s_and_b64 vcc, exec, s[46:47]
	s_cbranch_vccz .LBB0_302
	s_barrier

; #define PG8_STAGE(bufoff, gbase, voff) do { _Pragma("unroll") for (int _i = 0; _i < 2; ++_i) \
;         __builtin_amdgcn_global_load_lds((const unsigned*)((const char*)(gbase) + (voff)[_i]), (PG8_LAS unsigned*)(lds + (bufoff) + ldsw + _i * 8192), 16, 0, 0); } while (0)
; #define PG8_LDA(dst, b, h) do { _Pragma("unroll") for (int m = 0; m < 4; ++m) _Pragma("unroll") for (int k = 0; k < 2; ++k) dst[m][k] = *(const PG8_LAS bf16x8*)(lds + PG8_SA(b, h) + aoff + m * 2048 + k * 1024); } while (0)
; #define PG8_LDB(dst, b, h) do { _Pragma("unroll") for (int n = 0; n < 2; ++n) _Pragma("unroll") for (int k = 0; k < 2; ++k) dst[n][k] = *(const PG8_LAS bf16x8*)(lds + PG8_SB(b, h) + boff + n * 2048 + k * 1024); } while (0)
; #define PG8_MMA(ai, bj, At, Bt) do { __builtin_amdgcn_s_setprio(1); _Pragma("unroll") for (int m = 0; m < 4; ++m) _Pragma("unroll") for (int n = 0; n < 2; ++n) _Pragma("unroll") for (int k = 0; k < 2; ++k) \
;         acc[ai][bj][m][n] = __builtin_amdgcn_mfma_f32_16x16x32_bf16(Bt[n][k], At[m][k], acc[ai][bj][m][n], 0, 0, 0); __builtin_amdgcn_s_setprio(0); } while (0)
; #define PG8_WAIT_V(n) asm volatile("s_waitcnt vmcnt(" #n ")" ::: "memory")
; #define PG8_WAIT_L(n) asm volatile("s_waitcnt lgkmcnt(" #n ")" ::: "memory")
; template <class Epi, class Sched, bool ALIGN_EPI = false, bool SP2 = false>
; __device__ __forceinline__ void gemm_phase(PG8_LAS unsigned char* lds, const Gemm g, const Sched& S, const Epi& E) {
;     ...
;             const bool last = (t == nt - 2);
;             const char* a1 = cA + (size_t)(t + 1) * kstep;
;             const char* a2 = last ? nA : cA + (size_t)(t + 2) * kstep; const char* b2 = last ? nB : cB + (size_t)(t + 2) * kstep;
;             const char* a3 = a2 + kstep; const char* b3 = b2 + kstep;
;             if (last && has_next) S.a_ready(nxt);
;             if constexpr (SP2) {
;             PG8_LDB(B0, 0, 0); PG8_LDB(B1, 0, 1); PG8_SCHED; PG8_LDA(At, 0, 0); PG8_STAGE(PG8_SA(1, 1), a1 + hstep, voffA);
;             PG8_WAIT_V(8); PG8_WAIT_L(0); PG8_BAR; PG8_MMA(0, 0, At, B0); PG8_MMA(0, 1, At, B1); PG8_BAR; PG8_SCHED;
;             PG8_LDA(At, 0, 1); PG8_STAGE(PG8_SB(0, 0), b2, voffB); PG8_STAGE(PG8_SB(0, 1), b2 + hstep, voffB); PG8_STAGE(PG8_SA(0, 0), a2, voffA);
;             PG8_WAIT_V(8); PG8_WAIT_L(0); PG8_BAR; PG8_MMA(1, 0, At, B0); PG8_MMA(1, 1, At, B1); PG8_BAR; PG8_SCHED;
.LBB0_387:
	s_add_u32 s4, s56, 0xfff80080
	s_addc_u32 s5, s57, -1
	s_add_i32 s6, 0, 0x10000
	s_cmp_eq_u32 s20, 28
	s_cselect_b32 s59, s47, s5
	s_cselect_b32 s58, s75, s4
	v_add_u32_e32 v156, s6, v153
	s_cselect_b32 s55, s49, s77
	s_cselect_b32 s54, vcc_lo, s71
	s_add_i32 s4, 0, 0x14000
	ds_read_b128 v[144:147], v156
	ds_read_b128 v[148:151], v156 offset:1024
	ds_read_b128 v[168:171], v156 offset:2048
	ds_read_b128 v[172:175], v156 offset:3072
	v_add_u32_e32 v156, s4, v153
	ds_read_b128 v[176:179], v156
	ds_read_b128 v[180:183], v156 offset:1024
	ds_read_b128 v[184:187], v156 offset:2048
	ds_read_b128 v[188:191], v156 offset:3072
	v_lshl_add_u64 v[156:157], s[56:57], 0, v[140:141]
	s_add_i32 m0, s60, 0xc000
	ds_read_b128 v[212:215], v155
	ds_read_b128 v[216:219], v155 offset:1024
	ds_read_b128 v[220:223], v155 offset:2048
	ds_read_b128 v[224:227], v155 offset:3072
	ds_read_b128 v[228:231], v155 offset:4096
	ds_read_b128 v[232:235], v155 offset:5120
	ds_read_b128 v[236:239], v155 offset:6144
	ds_read_b128 v[240:243], v155 offset:7168
	global_load_lds_dwordx4 v[156:157], off
	v_lshl_add_u64 v[156:157], s[56:57], 0, v[142:143]
	s_add_i32 m0, s60, 0xe000
	s_nop 0
	global_load_lds_dwordx4 v[156:157], off
	s_waitcnt vmcnt(8)
	s_waitcnt lgkmcnt(0)
	s_barrier
	v_mfma_f32_16x16x32_bf16 v[122:125], v[144:147], v[212:215], v[122:125]
	v_mfma_f32_16x16x32_bf16 v[118:121], v[168:171], v[212:215], v[118:121]
	v_mfma_f32_16x16x32_bf16 v[106:109], v[144:147], v[220:223], v[106:109]
	v_mfma_f32_16x16x32_bf16 v[102:105], v[168:171], v[220:223], v[102:105]
	v_mfma_f32_16x16x32_bf16 v[90:93], v[144:147], v[228:231], v[90:93]
	v_mfma_f32_16x16x32_bf16 v[86:89], v[168:171], v[228:231], v[86:89]
	v_mfma_f32_16x16x32_bf16 v[74:77], v[144:147], v[236:239], v[74:77]
	v_mfma_f32_16x16x32_bf16 v[70:73], v[168:171], v[236:239], v[70:73]
	v_mfma_f32_16x16x32_bf16 v[122:125], v[148:151], v[216:219], v[122:125]
	v_mfma_f32_16x16x32_bf16 v[118:121], v[172:175], v[216:219], v[118:121]
	v_mfma_f32_16x16x32_bf16 v[106:109], v[148:151], v[224:227], v[106:109]
	v_mfma_f32_16x16x32_bf16 v[102:105], v[172:175], v[224:227], v[102:105]
	v_mfma_f32_16x16x32_bf16 v[90:93], v[148:151], v[232:235], v[90:93]
	v_mfma_f32_16x16x32_bf16 v[86:89], v[172:175], v[232:235], v[86:89]
	v_mfma_f32_16x16x32_bf16 v[74:77], v[148:151], v[240:243], v[74:77]
	v_mfma_f32_16x16x32_bf16 v[70:73], v[172:175], v[240:243], v[70:73]
	v_mfma_f32_16x16x32_bf16 v[130:133], v[176:179], v[212:215], v[130:133]
	v_mfma_f32_16x16x32_bf16 v[126:129], v[184:187], v[212:215], v[126:129]
	v_mfma_f32_16x16x32_bf16 v[114:117], v[176:179], v[220:223], v[114:117]
	v_mfma_f32_16x16x32_bf16 v[110:113], v[184:187], v[220:223], v[110:113]
	v_mfma_f32_16x16x32_bf16 v[98:101], v[176:179], v[228:231], v[98:101]
	v_mfma_f32_16x16x32_bf16 v[94:97], v[184:187], v[228:231], v[94:97]
	v_mfma_f32_16x16x32_bf16 v[82:85], v[176:179], v[236:239], v[82:85]
	v_mfma_f32_16x16x32_bf16 v[78:81], v[184:187], v[236:239], v[78:81]
	v_mfma_f32_16x16x32_bf16 v[130:133], v[180:183], v[216:219], v[130:133]
	v_mfma_f32_16x16x32_bf16 v[126:129], v[188:191], v[216:219], v[126:129]
	v_mfma_f32_16x16x32_bf16 v[114:117], v[180:183], v[224:227], v[114:117]
	v_mfma_f32_16x16x32_bf16 v[110:113], v[188:191], v[224:227], v[110:113]
	v_mfma_f32_16x16x32_bf16 v[98:101], v[180:183], v[232:235], v[98:101]
	v_mfma_f32_16x16x32_bf16 v[94:97], v[188:191], v[232:235], v[94:97]
	v_mfma_f32_16x16x32_bf16 v[82:85], v[180:183], v[240:243], v[82:85]
	v_mfma_f32_16x16x32_bf16 v[78:81], v[188:191], v[240:243], v[78:81]
	s_barrier
	s_add_i32 s5, s6, s24
	v_lshl_add_u64 v[156:157], s[54:55], 0, v[4:5]
	s_mov_b32 m0, s5
	ds_read_b128 v[212:215], v155 offset:16384
	ds_read_b128 v[216:219], v155 offset:17408
	ds_read_b128 v[220:223], v155 offset:18432
	ds_read_b128 v[224:227], v155 offset:19456
	ds_read_b128 v[228:231], v155 offset:20480
	ds_read_b128 v[232:235], v155 offset:21504
	ds_read_b128 v[236:239], v155 offset:22528
	ds_read_b128 v[240:243], v155 offset:23552
	global_load_lds_dwordx4 v[156:157], off
	s_add_i32 m0, s5, 0x2000
	s_add_u32 s34, s54, 0x80000
	v_lshl_add_u64 v[192:193], s[54:55], 0, v[2:3]
	s_addc_u32 s35, s55, 0
	s_add_i32 s4, s4, s24
	global_load_lds_dwordx4 v[192:193], off
	v_lshl_add_u64 v[244:245], s[34:35], 0, v[4:5]
	s_mov_b32 m0, s4
	v_lshl_add_u64 v[246:247], s[58:59], 0, v[134:135]
	global_load_lds_dwordx4 v[244:245], off
	v_lshl_add_u64 v[244:245], s[34:35], 0, v[2:3]
	s_add_i32 m0, s4, 0x2000
	s_nop 0
	global_load_lds_dwordx4 v[244:245], off
	v_lshl_add_u64 v[244:245], s[58:59], 0, v[136:137]
	s_mov_b32 m0, s60
	s_nop 0
	global_load_lds_dwordx4 v[244:245], off
	s_mov_b32 m0, s61
	s_nop 0
	global_load_lds_dwordx4 v[246:247], off
	s_waitcnt vmcnt(8)
	s_waitcnt lgkmcnt(0)
	s_barrier
; #define PG8_STAGE(bufoff, gbase, voff) do { _Pragma("unroll") for (int _i = 0; _i < 2; ++_i) \
;         __builtin_amdgcn_global_load_lds((const unsigned*)((const char*)(gbase) + (voff)[_i]), (PG8_LAS unsigned*)(lds + (bufoff) + ldsw + _i * 8192), 16, 0, 0); } while (0)
; #define PG8_LDA(dst, b, h) do { _Pragma("unroll") for (int m = 0; m < 4; ++m) _Pragma("unroll") for (int k = 0; k < 2; ++k) dst[m][k] = *(const PG8_LAS bf16x8*)(lds + PG8_SA(b, h) + aoff + m * 2048 + k * 1024); } while (0)
; #define PG8_LDB(dst, b, h) do { _Pragma("unroll") for (int n = 0; n < 2; ++n) _Pragma("unroll") for (int k = 0; k < 2; ++k) dst[n][k] = *(const PG8_LAS bf16x8*)(lds + PG8_SB(b, h) + boff + n * 2048 + k * 1024); } while (0)
; #define PG8_MMA(ai, bj, At, Bt) do { __builtin_amdgcn_s_setprio(1); _Pragma("unroll") for (int m = 0; m < 4; ++m) _Pragma("unroll") for (int n = 0; n < 2; ++n) _Pragma("unroll") for (int k = 0; k < 2; ++k) \
;         acc[ai][bj][m][n] = __builtin_amdgcn_mfma_f32_16x16x32_bf16(Bt[n][k], At[m][k], acc[ai][bj][m][n], 0, 0, 0); __builtin_amdgcn_s_setprio(0); } while (0)
; #define PG8_WAIT_V(n) asm volatile("s_waitcnt vmcnt(" #n ")" ::: "memory")
; #define PG8_WAIT_L(n) asm volatile("s_waitcnt lgkmcnt(" #n ")" ::: "memory")
; #define PG8_BAR __builtin_amdgcn_s_barrier()
; #define PG8_SCHED __builtin_amdgcn_sched_barrier(0)
; template <class Epi, class Sched, bool ALIGN_EPI = false, bool SP2 = false>
; __device__ __forceinline__ void gemm_phase(PG8_LAS unsigned char* lds, const Gemm g, const Sched& S, const Epi& E) {
;     ...
;             PG8_WAIT_V(8); PG8_WAIT_L(0); PG8_BAR; PG8_MMA(1, 0, At, B0); PG8_MMA(1, 1, At, B1); PG8_BAR; PG8_SCHED;
;             PG8_LDB(B0, 1, 0); PG8_LDB(B1, 1, 1); PG8_SCHED; PG8_LDA(At, 1, 0); PG8_STAGE(PG8_SA(0, 1), a2 + hstep, voffA);
;             PG8_WAIT_V(8); PG8_WAIT_L(0); PG8_BAR; PG8_MMA(0, 0, At, B0); PG8_MMA(0, 1, At, B1); PG8_BAR; PG8_SCHED;
	v_mfma_f32_16x16x32_bf16 v[58:61], v[144:147], v[212:215], v[58:61]
	v_mfma_f32_16x16x32_bf16 v[54:57], v[168:171], v[212:215], v[54:57]
	v_mfma_f32_16x16x32_bf16 v[42:45], v[144:147], v[220:223], v[42:45]
	v_mfma_f32_16x16x32_bf16 v[38:41], v[168:171], v[220:223], v[38:41]
	v_mfma_f32_16x16x32_bf16 v[26:29], v[144:147], v[228:231], v[26:29]
	v_mfma_f32_16x16x32_bf16 v[22:25], v[168:171], v[228:231], v[22:25]
	v_mfma_f32_16x16x32_bf16 v[10:13], v[144:147], v[236:239], v[10:13]
	v_mfma_f32_16x16x32_bf16 v[6:9], v[168:171], v[236:239], v[6:9]
	v_mfma_f32_16x16x32_bf16 v[58:61], v[148:151], v[216:219], v[58:61]
	v_mfma_f32_16x16x32_bf16 v[54:57], v[172:175], v[216:219], v[54:57]
	v_mfma_f32_16x16x32_bf16 v[42:45], v[148:151], v[224:227], v[42:45]
	v_mfma_f32_16x16x32_bf16 v[38:41], v[172:175], v[224:227], v[38:41]
	v_mfma_f32_16x16x32_bf16 v[26:29], v[148:151], v[232:235], v[26:29]
	v_mfma_f32_16x16x32_bf16 v[22:25], v[172:175], v[232:235], v[22:25]
	v_mfma_f32_16x16x32_bf16 v[10:13], v[148:151], v[240:243], v[10:13]
	v_mfma_f32_16x16x32_bf16 v[6:9], v[172:175], v[240:243], v[6:9]
	v_mfma_f32_16x16x32_bf16 v[66:69], v[176:179], v[212:215], v[66:69]
	v_mfma_f32_16x16x32_bf16 v[62:65], v[184:187], v[212:215], v[62:65]
	v_mfma_f32_16x16x32_bf16 v[50:53], v[176:179], v[220:223], v[50:53]
	v_mfma_f32_16x16x32_bf16 v[46:49], v[184:187], v[220:223], v[46:49]
	v_mfma_f32_16x16x32_bf16 v[34:37], v[176:179], v[228:231], v[34:37]
	v_mfma_f32_16x16x32_bf16 v[30:33], v[184:187], v[228:231], v[30:33]
	v_mfma_f32_16x16x32_bf16 v[14:17], v[176:179], v[236:239], v[14:17]
	v_mfma_f32_16x16x32_bf16 v[18:21], v[184:187], v[236:239], v[18:21]
	v_mfma_f32_16x16x32_bf16 v[66:69], v[180:183], v[216:219], v[66:69]
	v_mfma_f32_16x16x32_bf16 v[62:65], v[188:191], v[216:219], v[62:65]
	v_mfma_f32_16x16x32_bf16 v[50:53], v[180:183], v[224:227], v[50:53]
	v_mfma_f32_16x16x32_bf16 v[46:49], v[188:191], v[224:227], v[46:49]
	v_mfma_f32_16x16x32_bf16 v[34:37], v[180:183], v[232:235], v[34:37]
	v_mfma_f32_16x16x32_bf16 v[30:33], v[188:191], v[232:235], v[30:33]
	v_mfma_f32_16x16x32_bf16 v[14:17], v[180:183], v[240:243], v[14:17]
	v_mfma_f32_16x16x32_bf16 v[18:21], v[188:191], v[240:243], v[18:21]
	s_barrier
	s_add_i32 s4, 0, 0x18000
	v_add_u32_e32 v158, s4, v153
	s_add_i32 s5, 0, 0x1c000
	ds_read_b128 v[144:147], v158
	ds_read_b128 v[148:151], v158 offset:1024
	ds_read_b128 v[168:171], v158 offset:2048
	ds_read_b128 v[172:175], v158 offset:3072
	v_add_u32_e32 v158, s5, v153
	ds_read_b128 v[176:179], v158
	ds_read_b128 v[180:183], v158 offset:1024
	ds_read_b128 v[184:187], v158 offset:2048
	ds_read_b128 v[188:191], v158 offset:3072
	s_add_u32 s34, s58, 0x80000
	s_addc_u32 s35, s59, 0
	s_mov_b32 m0, s64
	v_lshl_add_u64 v[248:249], s[34:35], 0, v[136:137]
	ds_read_b128 v[212:215], v155 offset:32768
	ds_read_b128 v[216:219], v155 offset:33792
	ds_read_b128 v[220:223], v155 offset:34816
	ds_read_b128 v[224:227], v155 offset:35840
	ds_read_b128 v[228:231], v155 offset:36864
	ds_read_b128 v[232:235], v155 offset:37888
	ds_read_b128 v[236:239], v155 offset:38912
	ds_read_b128 v[240:243], v155 offset:39936
	global_load_lds_dwordx4 v[248:249], off
	v_lshl_add_u64 v[248:249], s[34:35], 0, v[134:135]
	s_mov_b32 m0, s65
	s_nop 0
	global_load_lds_dwordx4 v[248:249], off
	s_waitcnt vmcnt(8)
	s_waitcnt lgkmcnt(0)
	s_barrier
	v_mfma_f32_16x16x32_bf16 v[122:125], v[144:147], v[212:215], v[122:125]
	v_mfma_f32_16x16x32_bf16 v[118:121], v[168:171], v[212:215], v[118:121]
	v_mfma_f32_16x16x32_bf16 v[106:109], v[144:147], v[220:223], v[106:109]
	v_mfma_f32_16x16x32_bf16 v[102:105], v[168:171], v[220:223], v[102:105]
	v_mfma_f32_16x16x32_bf16 v[90:93], v[144:147], v[228:231], v[90:93]
	v_mfma_f32_16x16x32_bf16 v[86:89], v[168:171], v[228:231], v[86:89]
	v_mfma_f32_16x16x32_bf16 v[74:77], v[144:147], v[236:239], v[74:77]
	v_mfma_f32_16x16x32_bf16 v[70:73], v[168:171], v[236:239], v[70:73]
	v_mfma_f32_16x16x32_bf16 v[122:125], v[148:151], v[216:219], v[122:125]
	v_mfma_f32_16x16x32_bf16 v[118:121], v[172:175], v[216:219], v[118:121]
	v_mfma_f32_16x16x32_bf16 v[106:109], v[148:151], v[224:227], v[106:109]
	v_mfma_f32_16x16x32_bf16 v[102:105], v[172:175], v[224:227], v[102:105]
	v_mfma_f32_16x16x32_bf16 v[90:93], v[148:151], v[232:235], v[90:93]
	v_mfma_f32_16x16x32_bf16 v[86:89], v[172:175], v[232:235], v[86:89]
	v_mfma_f32_16x16x32_bf16 v[74:77], v[148:151], v[240:243], v[74:77]
	v_mfma_f32_16x16x32_bf16 v[70:73], v[172:175], v[240:243], v[70:73]
	v_mfma_f32_16x16x32_bf16 v[130:133], v[176:179], v[212:215], v[130:133]
	v_mfma_f32_16x16x32_bf16 v[126:129], v[184:187], v[212:215], v[126:129]
	v_mfma_f32_16x16x32_bf16 v[114:117], v[176:179], v[220:223], v[114:117]
	v_mfma_f32_16x16x32_bf16 v[110:113], v[184:187], v[220:223], v[110:113]
	v_mfma_f32_16x16x32_bf16 v[98:101], v[176:179], v[228:231], v[98:101]
	v_mfma_f32_16x16x32_bf16 v[94:97], v[184:187], v[228:231], v[94:97]
	v_mfma_f32_16x16x32_bf16 v[82:85], v[176:179], v[236:239], v[82:85]
	v_mfma_f32_16x16x32_bf16 v[78:81], v[184:187], v[236:239], v[78:81]
	v_mfma_f32_16x16x32_bf16 v[130:133], v[180:183], v[216:219], v[130:133]
	v_mfma_f32_16x16x32_bf16 v[126:129], v[188:191], v[216:219], v[126:129]
	v_mfma_f32_16x16x32_bf16 v[114:117], v[180:183], v[224:227], v[114:117]
	v_mfma_f32_16x16x32_bf16 v[110:113], v[188:191], v[224:227], v[110:113]
	v_mfma_f32_16x16x32_bf16 v[98:101], v[180:183], v[232:235], v[98:101]
	v_mfma_f32_16x16x32_bf16 v[94:97], v[188:191], v[232:235], v[94:97]
	v_mfma_f32_16x16x32_bf16 v[82:85], v[180:183], v[240:243], v[82:85]
	v_mfma_f32_16x16x32_bf16 v[78:81], v[188:191], v[240:243], v[78:81]
	s_barrier
; #define PG8_STAGE(bufoff, gbase, voff) do { _Pragma("unroll") for (int _i = 0; _i < 2; ++_i) \
;         __builtin_amdgcn_global_load_lds((const unsigned*)((const char*)(gbase) + (voff)[_i]), (PG8_LAS unsigned*)(lds + (bufoff) + ldsw + _i * 8192), 16, 0, 0); } while (0)
; #define PG8_LDA(dst, b, h) do { _Pragma("unroll") for (int m = 0; m < 4; ++m) _Pragma("unroll") for (int k = 0; k < 2; ++k) dst[m][k] = *(const PG8_LAS bf16x8*)(lds + PG8_SA(b, h) + aoff + m * 2048 + k * 1024); } while (0)
; #define PG8_MMA(ai, bj, At, Bt) do { __builtin_amdgcn_s_setprio(1); _Pragma("unroll") for (int m = 0; m < 4; ++m) _Pragma("unroll") for (int n = 0; n < 2; ++n) _Pragma("unroll") for (int k = 0; k < 2; ++k) \
;         acc[ai][bj][m][n] = __builtin_amdgcn_mfma_f32_16x16x32_bf16(Bt[n][k], At[m][k], acc[ai][bj][m][n], 0, 0, 0); __builtin_amdgcn_s_setprio(0); } while (0)
; #define PG8_WAIT_V(n) asm volatile("s_waitcnt vmcnt(" #n ")" ::: "memory")
; #define PG8_WAIT_L(n) asm volatile("s_waitcnt lgkmcnt(" #n ")" ::: "memory")
; #define PG8_BAR __builtin_amdgcn_s_barrier()
; #define PG8_SCHED __builtin_amdgcn_sched_barrier(0)
; template <class Epi, class Sched, bool ALIGN_EPI = false, bool SP2 = false>
; __device__ __forceinline__ void gemm_phase(PG8_LAS unsigned char* lds, const Gemm g, const Sched& S, const Epi& E) {
;     ...
;             PG8_WAIT_V(8); PG8_WAIT_L(0); PG8_BAR; PG8_MMA(0, 0, At, B0); PG8_MMA(0, 1, At, B1); PG8_BAR; PG8_SCHED;
;             PG8_LDA(At, 1, 1); PG8_STAGE(PG8_SB(1, 0), b3, voffB); PG8_STAGE(PG8_SB(1, 1), b3 + hstep, voffB); PG8_STAGE(PG8_SA(1, 0), a3, voffA);
;             PG8_WAIT_V(8); PG8_WAIT_L(0); PG8_BAR; PG8_MMA(1, 0, At, B0); PG8_MMA(1, 1, At, B1); PG8_BAR; PG8_SCHED;
	s_add_i32 s4, s4, s24
	v_lshl_add_u64 v[156:157], v[156:157], 0, s[28:29]
	s_mov_b32 m0, s4
	ds_read_b128 v[212:215], v155 offset:49152
	ds_read_b128 v[216:219], v155 offset:50176
	ds_read_b128 v[220:223], v155 offset:51200
	ds_read_b128 v[224:227], v155 offset:52224
	ds_read_b128 v[228:231], v155 offset:53248
	ds_read_b128 v[232:235], v155 offset:54272
	ds_read_b128 v[236:239], v155 offset:55296
	ds_read_b128 v[240:243], v155 offset:56320
	global_load_lds_dwordx4 v[156:157], off
	s_add_i32 m0, s4, 0x2000
	s_add_u32 s34, s54, 0x80080
	v_lshl_add_u64 v[156:157], v[192:193], 0, s[28:29]
	s_addc_u32 s35, s55, 0
	s_add_i32 s4, s5, s24
	global_load_lds_dwordx4 v[156:157], off
	v_lshl_add_u64 v[156:157], s[34:35], 0, v[4:5]
	s_mov_b32 m0, s4
	s_nop 0
	global_load_lds_dwordx4 v[156:157], off
	v_lshl_add_u64 v[156:157], s[34:35], 0, v[2:3]
	s_add_i32 m0, s4, 0x2000
	s_nop 0
	global_load_lds_dwordx4 v[156:157], off
	v_lshl_add_u64 v[156:157], v[244:245], 0, s[28:29]
	s_mov_b32 m0, s67
	s_nop 0
	global_load_lds_dwordx4 v[156:157], off
	v_lshl_add_u64 v[156:157], v[246:247], 0, s[28:29]
	s_mov_b32 m0, s72
	s_nop 0
	global_load_lds_dwordx4 v[156:157], off
	s_waitcnt vmcnt(8)
	s_waitcnt lgkmcnt(0)
	s_barrier
	v_mfma_f32_16x16x32_bf16 v[58:61], v[144:147], v[212:215], v[58:61]
	v_mfma_f32_16x16x32_bf16 v[54:57], v[168:171], v[212:215], v[54:57]
	v_mfma_f32_16x16x32_bf16 v[42:45], v[144:147], v[220:223], v[42:45]
	v_mfma_f32_16x16x32_bf16 v[38:41], v[168:171], v[220:223], v[38:41]
	v_mfma_f32_16x16x32_bf16 v[26:29], v[144:147], v[228:231], v[26:29]
	v_mfma_f32_16x16x32_bf16 v[22:25], v[168:171], v[228:231], v[22:25]
	v_mfma_f32_16x16x32_bf16 v[10:13], v[144:147], v[236:239], v[10:13]
	v_mfma_f32_16x16x32_bf16 v[6:9], v[168:171], v[236:239], v[6:9]
	v_mfma_f32_16x16x32_bf16 v[58:61], v[148:151], v[216:219], v[58:61]
	v_mfma_f32_16x16x32_bf16 v[54:57], v[172:175], v[216:219], v[54:57]
	v_mfma_f32_16x16x32_bf16 v[42:45], v[148:151], v[224:227], v[42:45]
	v_mfma_f32_16x16x32_bf16 v[38:41], v[172:175], v[224:227], v[38:41]
	v_mfma_f32_16x16x32_bf16 v[26:29], v[148:151], v[232:235], v[26:29]
	v_mfma_f32_16x16x32_bf16 v[22:25], v[172:175], v[232:235], v[22:25]
	v_mfma_f32_16x16x32_bf16 v[10:13], v[148:151], v[240:243], v[10:13]
	v_mfma_f32_16x16x32_bf16 v[6:9], v[172:175], v[240:243], v[6:9]
	v_mfma_f32_16x16x32_bf16 v[66:69], v[176:179], v[212:215], v[66:69]
	v_mfma_f32_16x16x32_bf16 v[62:65], v[184:187], v[212:215], v[62:65]
	v_mfma_f32_16x16x32_bf16 v[50:53], v[176:179], v[220:223], v[50:53]
	v_mfma_f32_16x16x32_bf16 v[46:49], v[184:187], v[220:223], v[46:49]
	v_mfma_f32_16x16x32_bf16 v[34:37], v[176:179], v[228:231], v[34:37]
	v_mfma_f32_16x16x32_bf16 v[30:33], v[184:187], v[228:231], v[30:33]
	v_mfma_f32_16x16x32_bf16 v[14:17], v[176:179], v[236:239], v[14:17]
	v_mfma_f32_16x16x32_bf16 v[18:21], v[184:187], v[236:239], v[18:21]
	v_mfma_f32_16x16x32_bf16 v[66:69], v[180:183], v[216:219], v[66:69]
	v_mfma_f32_16x16x32_bf16 v[62:65], v[188:191], v[216:219], v[62:65]
	v_mfma_f32_16x16x32_bf16 v[50:53], v[180:183], v[224:227], v[50:53]
	v_mfma_f32_16x16x32_bf16 v[46:49], v[188:191], v[224:227], v[46:49]
	v_mfma_f32_16x16x32_bf16 v[34:37], v[180:183], v[232:235], v[34:37]
	v_mfma_f32_16x16x32_bf16 v[30:33], v[188:191], v[232:235], v[30:33]
	v_mfma_f32_16x16x32_bf16 v[14:17], v[180:183], v[240:243], v[14:17]
	v_mfma_f32_16x16x32_bf16 v[18:21], v[188:191], v[240:243], v[18:21]
	s_barrier
	s_add_i32 s20, s20, 2
	s_add_u32 s56, s56, 0x100
	s_addc_u32 s57, s57, 0
	s_add_u32 s71, s71, 0x100
	s_addc_u32 s77, s77, 0
	s_cmp_gt_u32 s20, 29
	s_cbranch_scc0 .LBB0_387
	s_and_b64 vcc, exec, s[44:45]
	s_movk_i32 s75, 0x800
	s_movk_i32 s77, 0x6000
	s_mov_b32 s71, 0x44800000
	s_cbranch_vccz .LBB0_390
	s_barrier

; #define PG8_STAGE(bufoff, gbase, voff) do { _Pragma("unroll") for (int _i = 0; _i < 2; ++_i) \
;         __builtin_amdgcn_global_load_lds((const unsigned*)((const char*)(gbase) + (voff)[_i]), (PG8_LAS unsigned*)(lds + (bufoff) + ldsw + _i * 8192), 16, 0, 0); } while (0)
; #define PG8_LDA(dst, b, h) do { _Pragma("unroll") for (int m = 0; m < 4; ++m) _Pragma("unroll") for (int k = 0; k < 2; ++k) dst[m][k] = *(const PG8_LAS bf16x8*)(lds + PG8_SA(b, h) + aoff + m * 2048 + k * 1024); } while (0)
; #define PG8_LDB(dst, b, h) do { _Pragma("unroll") for (int n = 0; n < 2; ++n) _Pragma("unroll") for (int k = 0; k < 2; ++k) dst[n][k] = *(const PG8_LAS bf16x8*)(lds + PG8_SB(b, h) + boff + n * 2048 + k * 1024); } while (0)
; #define PG8_MMA(ai, bj, At, Bt) do { __builtin_amdgcn_s_setprio(1); _Pragma("unroll") for (int m = 0; m < 4; ++m) _Pragma("unroll") for (int n = 0; n < 2; ++n) _Pragma("unroll") for (int k = 0; k < 2; ++k) \
;         acc[ai][bj][m][n] = __builtin_amdgcn_mfma_f32_16x16x32_bf16(Bt[n][k], At[m][k], acc[ai][bj][m][n], 0, 0, 0); __builtin_amdgcn_s_setprio(0); } while (0)
; #define PG8_WAIT_V(n) asm volatile("s_waitcnt vmcnt(" #n ")" ::: "memory")
; #define PG8_WAIT_L(n) asm volatile("s_waitcnt lgkmcnt(" #n ")" ::: "memory")
; template <class Epi, class Sched, bool ALIGN_EPI = false, bool SP2 = false>
; __device__ __forceinline__ void gemm_phase(PG8_LAS unsigned char* lds, const Gemm g, const Sched& S, const Epi& E) {
;     ...
;             const bool last = (t == nt - 2);
;             const char* a1 = cA + (size_t)(t + 1) * kstep;
;             const char* a2 = last ? nA : cA + (size_t)(t + 2) * kstep; const char* b2 = last ? nB : cB + (size_t)(t + 2) * kstep;
;             const char* a3 = a2 + kstep; const char* b3 = b2 + kstep;
;             if (last && has_next) S.a_ready(nxt);
;             if constexpr (SP2) {
;             PG8_LDB(B0, 0, 0); PG8_LDB(B1, 0, 1); PG8_SCHED; PG8_LDA(At, 0, 0); PG8_STAGE(PG8_SA(1, 1), a1 + hstep, voffA);
;             PG8_WAIT_V(8); PG8_WAIT_L(0); PG8_BAR; PG8_MMA(0, 0, At, B0); PG8_MMA(0, 1, At, B1); PG8_BAR; PG8_SCHED;
;             PG8_LDA(At, 0, 1); PG8_STAGE(PG8_SB(0, 0), b2, voffB); PG8_STAGE(PG8_SB(0, 1), b2 + hstep, voffB); PG8_STAGE(PG8_SA(0, 0), a2, voffA);
;             PG8_WAIT_V(8); PG8_WAIT_L(0); PG8_BAR; PG8_MMA(1, 0, At, B0); PG8_MMA(1, 1, At, B1); PG8_BAR; PG8_SCHED;
.LBB0_1738:
	s_add_u32 s4, s50, 0xfff80080
	s_addc_u32 s5, s51, -1
	s_add_i32 s6, 0, 0x10000
	s_cmp_eq_u32 s20, 28
	s_cselect_b32 s53, s43, s5
	s_cselect_b32 s52, s66, s4
	s_cselect_b32 s49, s45, s71
	s_cselect_b32 s48, s67, s69
	s_add_i32 s4, 0, 0x14000
	v_add_u32_e32 v146, s6, v158
	v_add_u32_e32 v180, s4, v158
	ds_read_b128 v[134:137], v146
	ds_read_b128 v[138:141], v146 offset:1024
	ds_read_b128 v[142:145], v146 offset:2048
	ds_read_b128 v[146:149], v146 offset:3072
	ds_read_b128 v[150:153], v180
	ds_read_b128 v[154:157], v180 offset:1024
	ds_read_b128 v[176:179], v180 offset:2048
	ds_read_b128 v[180:183], v180 offset:3072
	v_lshl_add_u64 v[234:235], s[50:51], 0, v[172:173]
	s_add_i32 m0, s54, 0xc000
	ds_read_b128 v[184:187], v188
	ds_read_b128 v[190:193], v188 offset:1024
	ds_read_b128 v[210:213], v188 offset:2048
	ds_read_b128 v[214:217], v188 offset:3072
	ds_read_b128 v[218:221], v188 offset:4096
	ds_read_b128 v[222:225], v188 offset:5120
	ds_read_b128 v[226:229], v188 offset:6144
	ds_read_b128 v[230:233], v188 offset:7168
	global_load_lds_dwordx4 v[234:235], off
	v_lshl_add_u64 v[234:235], s[50:51], 0, v[174:175]
	s_add_i32 m0, s54, 0xe000
	s_nop 0
	global_load_lds_dwordx4 v[234:235], off
	s_waitcnt vmcnt(8)
	s_waitcnt lgkmcnt(0)
	s_barrier
	v_mfma_f32_16x16x32_bf16 v[122:125], v[134:137], v[184:187], v[122:125]
	v_mfma_f32_16x16x32_bf16 v[118:121], v[142:145], v[184:187], v[118:121]
	v_mfma_f32_16x16x32_bf16 v[114:117], v[134:137], v[210:213], v[114:117]
	v_mfma_f32_16x16x32_bf16 v[106:109], v[142:145], v[210:213], v[106:109]
	v_mfma_f32_16x16x32_bf16 v[98:101], v[134:137], v[218:221], v[98:101]
	v_mfma_f32_16x16x32_bf16 v[90:93], v[142:145], v[218:221], v[90:93]
	v_mfma_f32_16x16x32_bf16 v[82:85], v[134:137], v[226:229], v[82:85]
	v_mfma_f32_16x16x32_bf16 v[74:77], v[142:145], v[226:229], v[74:77]
	v_mfma_f32_16x16x32_bf16 v[122:125], v[138:141], v[190:193], v[122:125]
	v_mfma_f32_16x16x32_bf16 v[118:121], v[146:149], v[190:193], v[118:121]
	v_mfma_f32_16x16x32_bf16 v[114:117], v[138:141], v[214:217], v[114:117]
	v_mfma_f32_16x16x32_bf16 v[106:109], v[146:149], v[214:217], v[106:109]
	v_mfma_f32_16x16x32_bf16 v[98:101], v[138:141], v[222:225], v[98:101]
	v_mfma_f32_16x16x32_bf16 v[90:93], v[146:149], v[222:225], v[90:93]
	v_mfma_f32_16x16x32_bf16 v[82:85], v[138:141], v[230:233], v[82:85]
	v_mfma_f32_16x16x32_bf16 v[74:77], v[146:149], v[230:233], v[74:77]
	v_mfma_f32_16x16x32_bf16 v[130:133], v[150:153], v[184:187], v[130:133]
	v_mfma_f32_16x16x32_bf16 v[126:129], v[176:179], v[184:187], v[126:129]
	v_mfma_f32_16x16x32_bf16 v[110:113], v[150:153], v[210:213], v[110:113]
	v_mfma_f32_16x16x32_bf16 v[102:105], v[176:179], v[210:213], v[102:105]
	v_mfma_f32_16x16x32_bf16 v[94:97], v[150:153], v[218:221], v[94:97]
	v_mfma_f32_16x16x32_bf16 v[86:89], v[176:179], v[218:221], v[86:89]
	v_mfma_f32_16x16x32_bf16 v[78:81], v[150:153], v[226:229], v[78:81]
	v_mfma_f32_16x16x32_bf16 v[70:73], v[176:179], v[226:229], v[70:73]
	v_mfma_f32_16x16x32_bf16 v[130:133], v[154:157], v[190:193], v[130:133]
	v_mfma_f32_16x16x32_bf16 v[126:129], v[180:183], v[190:193], v[126:129]
	v_mfma_f32_16x16x32_bf16 v[110:113], v[154:157], v[214:217], v[110:113]
	v_mfma_f32_16x16x32_bf16 v[102:105], v[180:183], v[214:217], v[102:105]
	v_mfma_f32_16x16x32_bf16 v[94:97], v[154:157], v[222:225], v[94:97]
	v_mfma_f32_16x16x32_bf16 v[86:89], v[180:183], v[222:225], v[86:89]
	v_mfma_f32_16x16x32_bf16 v[78:81], v[154:157], v[230:233], v[78:81]
	v_mfma_f32_16x16x32_bf16 v[70:73], v[180:183], v[230:233], v[70:73]
	s_barrier
	s_add_i32 s5, s6, s24
	v_lshl_add_u64 v[234:235], s[48:49], 0, v[4:5]
	s_mov_b32 m0, s5
	ds_read_b128 v[184:187], v188 offset:16384
	ds_read_b128 v[190:193], v188 offset:17408
	ds_read_b128 v[210:213], v188 offset:18432
	ds_read_b128 v[214:217], v188 offset:19456
	ds_read_b128 v[218:221], v188 offset:20480
	ds_read_b128 v[222:225], v188 offset:21504
	ds_read_b128 v[226:229], v188 offset:22528
	ds_read_b128 v[230:233], v188 offset:23552
	global_load_lds_dwordx4 v[234:235], off
	s_add_i32 m0, s5, 0x2000
	s_add_u32 s34, s48, 0x80000
	v_lshl_add_u64 v[236:237], s[48:49], 0, v[2:3]
	s_addc_u32 s35, s49, 0
	s_add_i32 s4, s4, s24
	global_load_lds_dwordx4 v[236:237], off
	v_lshl_add_u64 v[238:239], s[34:35], 0, v[4:5]
	s_mov_b32 m0, s4
	v_lshl_add_u64 v[240:241], s[52:53], 0, v[168:169]
	global_load_lds_dwordx4 v[238:239], off
	v_lshl_add_u64 v[238:239], s[34:35], 0, v[2:3]
	s_add_i32 m0, s4, 0x2000
	s_nop 0
	global_load_lds_dwordx4 v[238:239], off
	v_lshl_add_u64 v[238:239], s[52:53], 0, v[170:171]
	s_mov_b32 m0, s54
	s_nop 0
	global_load_lds_dwordx4 v[238:239], off
	s_mov_b32 m0, s55
	s_nop 0
	global_load_lds_dwordx4 v[240:241], off
	s_waitcnt vmcnt(8)
	s_waitcnt lgkmcnt(0)
	s_barrier
; #define PG8_STAGE(bufoff, gbase, voff) do { _Pragma("unroll") for (int _i = 0; _i < 2; ++_i) \
;         __builtin_amdgcn_global_load_lds((const unsigned*)((const char*)(gbase) + (voff)[_i]), (PG8_LAS unsigned*)(lds + (bufoff) + ldsw + _i * 8192), 16, 0, 0); } while (0)
; #define PG8_LDA(dst, b, h) do { _Pragma("unroll") for (int m = 0; m < 4; ++m) _Pragma("unroll") for (int k = 0; k < 2; ++k) dst[m][k] = *(const PG8_LAS bf16x8*)(lds + PG8_SA(b, h) + aoff + m * 2048 + k * 1024); } while (0)
; #define PG8_LDB(dst, b, h) do { _Pragma("unroll") for (int n = 0; n < 2; ++n) _Pragma("unroll") for (int k = 0; k < 2; ++k) dst[n][k] = *(const PG8_LAS bf16x8*)(lds + PG8_SB(b, h) + boff + n * 2048 + k * 1024); } while (0)
; #define PG8_MMA(ai, bj, At, Bt) do { __builtin_amdgcn_s_setprio(1); _Pragma("unroll") for (int m = 0; m < 4; ++m) _Pragma("unroll") for (int n = 0; n < 2; ++n) _Pragma("unroll") for (int k = 0; k < 2; ++k) \
;         acc[ai][bj][m][n] = __builtin_amdgcn_mfma_f32_16x16x32_bf16(Bt[n][k], At[m][k], acc[ai][bj][m][n], 0, 0, 0); __builtin_amdgcn_s_setprio(0); } while (0)
; #define PG8_WAIT_V(n) asm volatile("s_waitcnt vmcnt(" #n ")" ::: "memory")
; #define PG8_WAIT_L(n) asm volatile("s_waitcnt lgkmcnt(" #n ")" ::: "memory")
; #define PG8_BAR __builtin_amdgcn_s_barrier()
; #define PG8_SCHED __builtin_amdgcn_sched_barrier(0)
; template <class Epi, class Sched, bool ALIGN_EPI = false, bool SP2 = false>
; __device__ __forceinline__ void gemm_phase(PG8_LAS unsigned char* lds, const Gemm g, const Sched& S, const Epi& E) {
;     ...
;             PG8_WAIT_V(8); PG8_WAIT_L(0); PG8_BAR; PG8_MMA(1, 0, At, B0); PG8_MMA(1, 1, At, B1); PG8_BAR; PG8_SCHED;
;             PG8_LDB(B0, 1, 0); PG8_LDB(B1, 1, 1); PG8_SCHED; PG8_LDA(At, 1, 0); PG8_STAGE(PG8_SA(0, 1), a2 + hstep, voffA);
;             PG8_WAIT_V(8); PG8_WAIT_L(0); PG8_BAR; PG8_MMA(0, 0, At, B0); PG8_MMA(0, 1, At, B1); PG8_BAR; PG8_SCHED;
	v_mfma_f32_16x16x32_bf16 v[58:61], v[134:137], v[184:187], v[58:61]
	v_mfma_f32_16x16x32_bf16 v[54:57], v[142:145], v[184:187], v[54:57]
	v_mfma_f32_16x16x32_bf16 v[50:53], v[134:137], v[210:213], v[50:53]
	v_mfma_f32_16x16x32_bf16 v[42:45], v[142:145], v[210:213], v[42:45]
	v_mfma_f32_16x16x32_bf16 v[34:37], v[134:137], v[218:221], v[34:37]
	v_mfma_f32_16x16x32_bf16 v[26:29], v[142:145], v[218:221], v[26:29]
	v_mfma_f32_16x16x32_bf16 v[18:21], v[134:137], v[226:229], v[18:21]
	v_mfma_f32_16x16x32_bf16 v[10:13], v[142:145], v[226:229], v[10:13]
	v_mfma_f32_16x16x32_bf16 v[58:61], v[138:141], v[190:193], v[58:61]
	v_mfma_f32_16x16x32_bf16 v[54:57], v[146:149], v[190:193], v[54:57]
	v_mfma_f32_16x16x32_bf16 v[50:53], v[138:141], v[214:217], v[50:53]
	v_mfma_f32_16x16x32_bf16 v[42:45], v[146:149], v[214:217], v[42:45]
	v_mfma_f32_16x16x32_bf16 v[34:37], v[138:141], v[222:225], v[34:37]
	v_mfma_f32_16x16x32_bf16 v[26:29], v[146:149], v[222:225], v[26:29]
	v_mfma_f32_16x16x32_bf16 v[18:21], v[138:141], v[230:233], v[18:21]
	v_mfma_f32_16x16x32_bf16 v[10:13], v[146:149], v[230:233], v[10:13]
	v_mfma_f32_16x16x32_bf16 v[66:69], v[150:153], v[184:187], v[66:69]
	v_mfma_f32_16x16x32_bf16 v[62:65], v[176:179], v[184:187], v[62:65]
	v_mfma_f32_16x16x32_bf16 v[46:49], v[150:153], v[210:213], v[46:49]
	v_mfma_f32_16x16x32_bf16 v[38:41], v[176:179], v[210:213], v[38:41]
	v_mfma_f32_16x16x32_bf16 v[30:33], v[150:153], v[218:221], v[30:33]
	v_mfma_f32_16x16x32_bf16 v[22:25], v[176:179], v[218:221], v[22:25]
	v_mfma_f32_16x16x32_bf16 v[14:17], v[150:153], v[226:229], v[14:17]
	v_mfma_f32_16x16x32_bf16 v[6:9], v[176:179], v[226:229], v[6:9]
	v_mfma_f32_16x16x32_bf16 v[66:69], v[154:157], v[190:193], v[66:69]
	v_mfma_f32_16x16x32_bf16 v[62:65], v[180:183], v[190:193], v[62:65]
	v_mfma_f32_16x16x32_bf16 v[46:49], v[154:157], v[214:217], v[46:49]
	v_mfma_f32_16x16x32_bf16 v[38:41], v[180:183], v[214:217], v[38:41]
	v_mfma_f32_16x16x32_bf16 v[30:33], v[154:157], v[222:225], v[30:33]
	v_mfma_f32_16x16x32_bf16 v[22:25], v[180:183], v[222:225], v[22:25]
	v_mfma_f32_16x16x32_bf16 v[14:17], v[154:157], v[230:233], v[14:17]
	v_mfma_f32_16x16x32_bf16 v[6:9], v[180:183], v[230:233], v[6:9]
	s_barrier
	s_add_i32 s4, 0, 0x18000
	s_add_i32 s5, 0, 0x1c000
	v_add_u32_e32 v146, s4, v158
	v_add_u32_e32 v180, s5, v158
	ds_read_b128 v[134:137], v146
	ds_read_b128 v[138:141], v146 offset:1024
	ds_read_b128 v[142:145], v146 offset:2048
	ds_read_b128 v[146:149], v146 offset:3072
	ds_read_b128 v[150:153], v180
	ds_read_b128 v[154:157], v180 offset:1024
	ds_read_b128 v[176:179], v180 offset:2048
	ds_read_b128 v[180:183], v180 offset:3072
	s_add_u32 s34, s52, 0x80000
	s_addc_u32 s35, s53, 0
	s_mov_b32 m0, s56
	v_lshl_add_u64 v[242:243], s[34:35], 0, v[170:171]
	ds_read_b128 v[184:187], v188 offset:32768
	ds_read_b128 v[190:193], v188 offset:33792
	ds_read_b128 v[210:213], v188 offset:34816
	ds_read_b128 v[214:217], v188 offset:35840
	ds_read_b128 v[218:221], v188 offset:36864
	ds_read_b128 v[222:225], v188 offset:37888
	ds_read_b128 v[226:229], v188 offset:38912
	ds_read_b128 v[230:233], v188 offset:39936
	global_load_lds_dwordx4 v[242:243], off
	v_lshl_add_u64 v[242:243], s[34:35], 0, v[168:169]
	s_mov_b32 m0, s57
	s_nop 0
	global_load_lds_dwordx4 v[242:243], off
	s_waitcnt vmcnt(8)
	s_waitcnt lgkmcnt(0)
	s_barrier
	v_mfma_f32_16x16x32_bf16 v[122:125], v[134:137], v[184:187], v[122:125]
	v_mfma_f32_16x16x32_bf16 v[118:121], v[142:145], v[184:187], v[118:121]
	v_mfma_f32_16x16x32_bf16 v[114:117], v[134:137], v[210:213], v[114:117]
	v_mfma_f32_16x16x32_bf16 v[106:109], v[142:145], v[210:213], v[106:109]
	v_mfma_f32_16x16x32_bf16 v[98:101], v[134:137], v[218:221], v[98:101]
	v_mfma_f32_16x16x32_bf16 v[90:93], v[142:145], v[218:221], v[90:93]
	v_mfma_f32_16x16x32_bf16 v[82:85], v[134:137], v[226:229], v[82:85]
	v_mfma_f32_16x16x32_bf16 v[74:77], v[142:145], v[226:229], v[74:77]
	v_mfma_f32_16x16x32_bf16 v[122:125], v[138:141], v[190:193], v[122:125]
	v_mfma_f32_16x16x32_bf16 v[118:121], v[146:149], v[190:193], v[118:121]
	v_mfma_f32_16x16x32_bf16 v[114:117], v[138:141], v[214:217], v[114:117]
	v_mfma_f32_16x16x32_bf16 v[106:109], v[146:149], v[214:217], v[106:109]
	v_mfma_f32_16x16x32_bf16 v[98:101], v[138:141], v[222:225], v[98:101]
	v_mfma_f32_16x16x32_bf16 v[90:93], v[146:149], v[222:225], v[90:93]
	v_mfma_f32_16x16x32_bf16 v[82:85], v[138:141], v[230:233], v[82:85]
	v_mfma_f32_16x16x32_bf16 v[74:77], v[146:149], v[230:233], v[74:77]
	v_mfma_f32_16x16x32_bf16 v[130:133], v[150:153], v[184:187], v[130:133]
	v_mfma_f32_16x16x32_bf16 v[126:129], v[176:179], v[184:187], v[126:129]
	v_mfma_f32_16x16x32_bf16 v[110:113], v[150:153], v[210:213], v[110:113]
	v_mfma_f32_16x16x32_bf16 v[102:105], v[176:179], v[210:213], v[102:105]
	v_mfma_f32_16x16x32_bf16 v[94:97], v[150:153], v[218:221], v[94:97]
	v_mfma_f32_16x16x32_bf16 v[86:89], v[176:179], v[218:221], v[86:89]
	v_mfma_f32_16x16x32_bf16 v[78:81], v[150:153], v[226:229], v[78:81]
	v_mfma_f32_16x16x32_bf16 v[70:73], v[176:179], v[226:229], v[70:73]
	v_mfma_f32_16x16x32_bf16 v[130:133], v[154:157], v[190:193], v[130:133]
	v_mfma_f32_16x16x32_bf16 v[126:129], v[180:183], v[190:193], v[126:129]
	v_mfma_f32_16x16x32_bf16 v[110:113], v[154:157], v[214:217], v[110:113]
	v_mfma_f32_16x16x32_bf16 v[102:105], v[180:183], v[214:217], v[102:105]
	v_mfma_f32_16x16x32_bf16 v[94:97], v[154:157], v[222:225], v[94:97]
	v_mfma_f32_16x16x32_bf16 v[86:89], v[180:183], v[222:225], v[86:89]
	v_mfma_f32_16x16x32_bf16 v[78:81], v[154:157], v[230:233], v[78:81]
	v_mfma_f32_16x16x32_bf16 v[70:73], v[180:183], v[230:233], v[70:73]
	s_barrier
; #define PG8_STAGE(bufoff, gbase, voff) do { _Pragma("unroll") for (int _i = 0; _i < 2; ++_i) \
;         __builtin_amdgcn_global_load_lds((const unsigned*)((const char*)(gbase) + (voff)[_i]), (PG8_LAS unsigned*)(lds + (bufoff) + ldsw + _i * 8192), 16, 0, 0); } while (0)
; #define PG8_LDA(dst, b, h) do { _Pragma("unroll") for (int m = 0; m < 4; ++m) _Pragma("unroll") for (int k = 0; k < 2; ++k) dst[m][k] = *(const PG8_LAS bf16x8*)(lds + PG8_SA(b, h) + aoff + m * 2048 + k * 1024); } while (0)
; #define PG8_MMA(ai, bj, At, Bt) do { __builtin_amdgcn_s_setprio(1); _Pragma("unroll") for (int m = 0; m < 4; ++m) _Pragma("unroll") for (int n = 0; n < 2; ++n) _Pragma("unroll") for (int k = 0; k < 2; ++k) \
;         acc[ai][bj][m][n] = __builtin_amdgcn_mfma_f32_16x16x32_bf16(Bt[n][k], At[m][k], acc[ai][bj][m][n], 0, 0, 0); __builtin_amdgcn_s_setprio(0); } while (0)
; #define PG8_WAIT_V(n) asm volatile("s_waitcnt vmcnt(" #n ")" ::: "memory")
; #define PG8_WAIT_L(n) asm volatile("s_waitcnt lgkmcnt(" #n ")" ::: "memory")
; #define PG8_BAR __builtin_amdgcn_s_barrier()
; #define PG8_SCHED __builtin_amdgcn_sched_barrier(0)
; template <class Epi, class Sched, bool ALIGN_EPI = false, bool SP2 = false>
; __device__ __forceinline__ void gemm_phase(PG8_LAS unsigned char* lds, const Gemm g, const Sched& S, const Epi& E) {
;     ...
;             PG8_WAIT_V(8); PG8_WAIT_L(0); PG8_BAR; PG8_MMA(0, 0, At, B0); PG8_MMA(0, 1, At, B1); PG8_BAR; PG8_SCHED;
;             PG8_LDA(At, 1, 1); PG8_STAGE(PG8_SB(1, 0), b3, voffB); PG8_STAGE(PG8_SB(1, 1), b3 + hstep, voffB); PG8_STAGE(PG8_SA(1, 0), a3, voffA);
;             PG8_WAIT_V(8); PG8_WAIT_L(0); PG8_BAR; PG8_MMA(1, 0, At, B0); PG8_MMA(1, 1, At, B1); PG8_BAR; PG8_SCHED;
	s_add_i32 s4, s4, s24
	v_lshl_add_u64 v[234:235], v[234:235], 0, s[28:29]
	s_mov_b32 m0, s4
	ds_read_b128 v[184:187], v188 offset:49152
	ds_read_b128 v[190:193], v188 offset:50176
	ds_read_b128 v[210:213], v188 offset:51200
	ds_read_b128 v[214:217], v188 offset:52224
	ds_read_b128 v[218:221], v188 offset:53248
	ds_read_b128 v[222:225], v188 offset:54272
	ds_read_b128 v[226:229], v188 offset:55296
	ds_read_b128 v[230:233], v188 offset:56320
	global_load_lds_dwordx4 v[234:235], off
	s_add_i32 m0, s4, 0x2000
	s_add_u32 s34, s48, 0x80080
	v_lshl_add_u64 v[234:235], v[236:237], 0, s[28:29]
	s_addc_u32 s35, s49, 0
	s_add_i32 s4, s5, s24
	global_load_lds_dwordx4 v[234:235], off
	v_lshl_add_u64 v[234:235], s[34:35], 0, v[4:5]
	s_mov_b32 m0, s4
	s_nop 0
	global_load_lds_dwordx4 v[234:235], off
	v_lshl_add_u64 v[234:235], s[34:35], 0, v[2:3]
	s_add_i32 m0, s4, 0x2000
	s_nop 0
	global_load_lds_dwordx4 v[234:235], off
	v_lshl_add_u64 v[234:235], v[238:239], 0, s[28:29]
	s_mov_b32 m0, s60
	s_nop 0
	global_load_lds_dwordx4 v[234:235], off
	v_lshl_add_u64 v[234:235], v[240:241], 0, s[28:29]
	s_mov_b32 m0, s61
	s_nop 0
	global_load_lds_dwordx4 v[234:235], off
	s_waitcnt vmcnt(8)
	s_waitcnt lgkmcnt(0)
	s_barrier
	v_mfma_f32_16x16x32_bf16 v[58:61], v[134:137], v[184:187], v[58:61]
	v_mfma_f32_16x16x32_bf16 v[54:57], v[142:145], v[184:187], v[54:57]
	v_mfma_f32_16x16x32_bf16 v[50:53], v[134:137], v[210:213], v[50:53]
	v_mfma_f32_16x16x32_bf16 v[42:45], v[142:145], v[210:213], v[42:45]
	v_mfma_f32_16x16x32_bf16 v[34:37], v[134:137], v[218:221], v[34:37]
	v_mfma_f32_16x16x32_bf16 v[26:29], v[142:145], v[218:221], v[26:29]
	v_mfma_f32_16x16x32_bf16 v[18:21], v[134:137], v[226:229], v[18:21]
	v_mfma_f32_16x16x32_bf16 v[10:13], v[142:145], v[226:229], v[10:13]
	v_mfma_f32_16x16x32_bf16 v[58:61], v[138:141], v[190:193], v[58:61]
	v_mfma_f32_16x16x32_bf16 v[54:57], v[146:149], v[190:193], v[54:57]
	v_mfma_f32_16x16x32_bf16 v[50:53], v[138:141], v[214:217], v[50:53]
	v_mfma_f32_16x16x32_bf16 v[42:45], v[146:149], v[214:217], v[42:45]
	v_mfma_f32_16x16x32_bf16 v[34:37], v[138:141], v[222:225], v[34:37]
	v_mfma_f32_16x16x32_bf16 v[26:29], v[146:149], v[222:225], v[26:29]
	v_mfma_f32_16x16x32_bf16 v[18:21], v[138:141], v[230:233], v[18:21]
	v_mfma_f32_16x16x32_bf16 v[10:13], v[146:149], v[230:233], v[10:13]
	v_mfma_f32_16x16x32_bf16 v[66:69], v[150:153], v[184:187], v[66:69]
	v_mfma_f32_16x16x32_bf16 v[62:65], v[176:179], v[184:187], v[62:65]
	v_mfma_f32_16x16x32_bf16 v[46:49], v[150:153], v[210:213], v[46:49]
	v_mfma_f32_16x16x32_bf16 v[38:41], v[176:179], v[210:213], v[38:41]
	v_mfma_f32_16x16x32_bf16 v[30:33], v[150:153], v[218:221], v[30:33]
	v_mfma_f32_16x16x32_bf16 v[22:25], v[176:179], v[218:221], v[22:25]
	v_mfma_f32_16x16x32_bf16 v[14:17], v[150:153], v[226:229], v[14:17]
	v_mfma_f32_16x16x32_bf16 v[6:9], v[176:179], v[226:229], v[6:9]
	v_mfma_f32_16x16x32_bf16 v[66:69], v[154:157], v[190:193], v[66:69]
	v_mfma_f32_16x16x32_bf16 v[62:65], v[180:183], v[190:193], v[62:65]
	v_mfma_f32_16x16x32_bf16 v[46:49], v[154:157], v[214:217], v[46:49]
	v_mfma_f32_16x16x32_bf16 v[38:41], v[180:183], v[214:217], v[38:41]
	v_mfma_f32_16x16x32_bf16 v[30:33], v[154:157], v[222:225], v[30:33]
	v_mfma_f32_16x16x32_bf16 v[22:25], v[180:183], v[222:225], v[22:25]
	v_mfma_f32_16x16x32_bf16 v[14:17], v[154:157], v[230:233], v[14:17]
	v_mfma_f32_16x16x32_bf16 v[6:9], v[180:183], v[230:233], v[6:9]
	s_barrier
	s_add_i32 s20, s20, 2
	s_add_u32 s50, s50, 0x100
	s_addc_u32 s51, s51, 0
	s_add_u32 s69, s69, 0x100
	s_addc_u32 s71, s71, 0
	s_cmp_gt_u32 s20, 29
	s_cbranch_scc0 .LBB0_1738
	s_and_b64 vcc, exec, s[40:41]
	s_cbranch_vccz .LBB0_1741
	s_barrier
